# MLA: tile writes one PV MFMA earlier in both streams (two MFMAs between the writes and the barrier)
# baseline (speedup 1.0000x reference)
; __device__ __forceinline__ void finishSM9(f32x16& p0, f32x16& p1, float alpha, float& l_reg, v8i32& p8) {
; #pragma unroll
;   for (int r = 0; r < 16; ++r) { p0[r] = __builtin_amdgcn_exp2f(p0[r]); p1[r] = __builtin_amdgcn_exp2f(p1[r]); }
;   float ps = 0;
; #pragma unroll
;   for (int r = 0; r < 16; ++r) ps += p0[r];
; #pragma unroll
;   for (int r = 0; r < 16; ++r) ps += p1[r];
;   { auto rr = __builtin_amdgcn_permlane32_swap(__float_as_uint(ps), __float_as_uint(ps), false, false);
;     ps = __uint_as_float(rr[0]) + __uint_as_float(rr[1]); }
;   l_reg = l_reg * alpha + ps;
; #pragma unroll
;   for (int g = 0; g < 4; ++g) {
;     int w = __builtin_amdgcn_cvt_pk_fp8_f32(p0[4 * g], p0[4 * g + 1], 0, false); p8[g] = __builtin_amdgcn_cvt_pk_fp8_f32(p0[4 * g + 2], p0[4 * g + 3], w, true);
;     int u = __builtin_amdgcn_cvt_pk_fp8_f32(p1[4 * g], p1[4 * g + 1], 0, false); p8[4 + g] = __builtin_amdgcn_cvt_pk_fp8_f32(p1[4 * g + 2], p1[4 * g + 3], u, true); }
; }
; __device__ __forceinline__ void pv8(f32x16* o, const char* Vt, const v8i32 p8, int r32, int hi) {
;   const int sw = (r32 >> 2) & 3, a0 = r32 * 64 + (((hi * 2) ^ sw) << 4), a1 = r32 * 64 + (((hi * 2 + 1) ^ sw) << 4);
; #pragma unroll
;   for (int d0 = 0; d0 < 4; ++d0) {
;     const v8i32 vf = cat8(*reinterpret_cast<const v4i32*>(Vt + d0 * 2048 + a0), *reinterpret_cast<const v4i32*>(Vt + d0 * 2048 + a1));
;     o[d0] = __builtin_amdgcn_mfma_scale_f32_32x32x64_f8f6f4(p8, vf, o[d0], 0, 0, 0, 127, 0, 127); }
; }
; __device__ __forceinline__ void qkt9(f32x16& p0, f32x16& p1, const char* Kn, const char* Kr, const v8i32* qf, const float init, int r32, int hi) {
; #pragma unroll
;   for (int r = 0; r < 16; ++r) { p0[r] = init; p1[r] = init; }
; #pragma unroll
;   for (int s = 0; s < 2; ++s) { const int c0 = s * 4 + hi * 2;
;     const v8i32 a0 = cat8(*reinterpret_cast<const v4i32*>(Kn + KN8SW(r32, c0)), *reinterpret_cast<const v4i32*>(Kn + KN8SW(r32, c0 + 1)));
;     const v8i32 a1 = cat8(*reinterpret_cast<const v4i32*>(Kn + 4096 + KN8SW(r32, c0)), *reinterpret_cast<const v4i32*>(Kn + 4096 + KN8SW(r32, c0 + 1)));
;     p0 = __builtin_amdgcn_mfma_scale_f32_32x32x64_f8f6f4(a0, qf[s], p0, 0, 0, 0, 127, 0, 124);
;     p1 = __builtin_amdgcn_mfma_scale_f32_32x32x64_f8f6f4(a1, qf[s], p1, 0, 0, 0, 127, 0, 124); }
;   { const int c0 = hi * 2;
.LBB0_1321:
	global_load_dwordx4 v[158:161], v176, s[18:19]
	global_load_dwordx4 v[162:165], v178, s[16:17]
	global_load_dwordx4 v[154:157], v[180:181], off
	ds_read_b128 v[114:117], v215 offset:24576
	ds_read_b128 v[118:121], v216 offset:24576
	ds_read_b128 v[222:225], v215 offset:28672
	ds_read_b128 v[226:229], v216 offset:28672
	v_add_u32_e32 v176, 0x2000, v176
	v_add_u32_e32 v178, 0x20000, v178
	s_mov_b64 s[20:21], 0x1000
	v_lshl_add_u64 v[180:181], v[180:181], 0, s[20:21]
	v_exp_f32_e32 v0, v82
	v_exp_f32_e32 v177, v83
	v_exp_f32_e32 v179, v84
	v_exp_f32_e32 v254, v85
	v_add_f32_e32 v219, v0, v177
	v_cvt_pk_fp8_f32 v246, v0, v177
	v_add_f32_e32 v219, v179, v219
	v_add_f32_e32 v219, v254, v219
	v_cvt_pk_fp8_f32 v246, v179, v254 op_sel:[0,0,1]
	s_waitcnt lgkmcnt(2)
	v_mfma_scale_f32_32x32x64_f8f6f4 v[114:129], v[114:121], v[146:153], v[230:245], v194, v193 op_sel_hi:[0,0,0]
	v_exp_f32_e32 v0, v86
	v_exp_f32_e32 v177, v87
	v_exp_f32_e32 v179, v88
	v_exp_f32_e32 v254, v89
	v_add_f32_e32 v219, v0, v219
	v_add_f32_e32 v219, v177, v219
	v_cvt_pk_fp8_f32 v247, v0, v177
	v_add_f32_e32 v219, v179, v219
	v_add_f32_e32 v219, v254, v219
	v_cvt_pk_fp8_f32 v247, v179, v254 op_sel:[0,0,1]
	ds_read_b128 v[82:85], v213 offset:24576
	ds_read_b128 v[86:89], v214 offset:24576
	s_waitcnt lgkmcnt(2)
	v_mfma_scale_f32_32x32x64_f8f6f4 v[98:113], v[222:229], v[146:153], v[230:245], v194, v193 op_sel_hi:[0,0,0]
	ds_read_b128 v[222:225], v213 offset:28672
	ds_read_b128 v[226:229], v214 offset:28672
	v_exp_f32_e32 v0, v90
	v_exp_f32_e32 v177, v91
	v_exp_f32_e32 v179, v92
	v_exp_f32_e32 v254, v93
	v_add_f32_e32 v219, v0, v219
	v_add_f32_e32 v219, v177, v219
	v_cvt_pk_fp8_f32 v248, v0, v177
	v_add_f32_e32 v219, v179, v219
	v_add_f32_e32 v219, v254, v219
	v_cvt_pk_fp8_f32 v248, v179, v254 op_sel:[0,0,1]
	v_exp_f32_e32 v0, v94
	v_exp_f32_e32 v177, v95
	v_exp_f32_e32 v179, v96
	v_exp_f32_e32 v254, v97
	v_add_f32_e32 v219, v0, v219
	v_add_f32_e32 v219, v177, v219
	v_cvt_pk_fp8_f32 v249, v0, v177
	v_add_f32_e32 v219, v179, v219
	v_add_f32_e32 v219, v254, v219
	v_cvt_pk_fp8_f32 v249, v179, v254 op_sel:[0,0,1]
	ds_read_b128 v[90:93], v185 offset:36864
	ds_read_b128 v[94:97], v186 offset:36864
	s_waitcnt lgkmcnt(4)
	v_mfma_scale_f32_32x32x64_f8f6f4 v[114:129], v[82:89], v[138:145], v[114:129], v194, v193 op_sel_hi:[0,0,0]
	v_exp_f32_e32 v0, v66
	v_exp_f32_e32 v177, v67
	v_exp_f32_e32 v179, v68
	v_exp_f32_e32 v254, v69
	v_add_f32_e32 v219, v0, v219
	v_add_f32_e32 v219, v177, v219
	v_cvt_pk_fp8_f32 v250, v0, v177
	v_add_f32_e32 v219, v179, v219
	v_add_f32_e32 v219, v254, v219
	v_cvt_pk_fp8_f32 v250, v179, v254 op_sel:[0,0,1]
	s_waitcnt lgkmcnt(2)
	v_mfma_scale_f32_32x32x64_f8f6f4 v[98:113], v[222:229], v[138:145], v[98:113], v194, v193 op_sel_hi:[0,0,0]
	ds_read_b128 v[222:225], v185 offset:38912
	ds_read_b128 v[226:229], v186 offset:38912
	v_exp_f32_e32 v0, v70
	v_exp_f32_e32 v177, v71
	v_exp_f32_e32 v179, v72
	v_exp_f32_e32 v254, v73
	v_add_f32_e32 v219, v0, v219
	v_add_f32_e32 v219, v177, v219
	v_cvt_pk_fp8_f32 v251, v0, v177
	v_add_f32_e32 v219, v179, v219
	v_add_f32_e32 v219, v254, v219
	v_cvt_pk_fp8_f32 v251, v179, v254 op_sel:[0,0,1]
	v_exp_f32_e32 v0, v74
	v_exp_f32_e32 v177, v75
	v_exp_f32_e32 v179, v76
	v_exp_f32_e32 v254, v77
	v_add_f32_e32 v219, v0, v219
	v_add_f32_e32 v219, v177, v219
	v_cvt_pk_fp8_f32 v252, v0, v177
	v_add_f32_e32 v219, v179, v219
	v_add_f32_e32 v219, v254, v219
	v_cvt_pk_fp8_f32 v252, v179, v254 op_sel:[0,0,1]
	s_waitcnt lgkmcnt(2)
	v_mfma_scale_f32_32x32x64_f8f6f4 v[114:129], v[90:97], v[130:137], v[114:129], v194, v193 op_sel_hi:[0,0,0]
	v_exp_f32_e32 v0, v78
	v_exp_f32_e32 v177, v79
	v_exp_f32_e32 v179, v80
	v_exp_f32_e32 v254, v81
	v_add_f32_e32 v219, v0, v219
	v_add_f32_e32 v219, v177, v219
	v_cvt_pk_fp8_f32 v253, v0, v177
	v_add_f32_e32 v219, v179, v219
	v_add_f32_e32 v219, v254, v219
	v_cvt_pk_fp8_f32 v253, v179, v254 op_sel:[0,0,1]
	ds_read_b128 v[90:93], v185 offset:0
	ds_read_b128 v[94:97], v186 offset:0
	ds_read_b128 v[82:85], v185 offset:2048
	ds_read_b128 v[86:89], v186 offset:2048
	ds_read_b128 v[74:77], v185 offset:4096
	ds_read_b128 v[78:81], v186 offset:4096
	ds_read_b128 v[66:69], v185 offset:6144
	ds_read_b128 v[70:73], v186 offset:6144
	s_waitcnt lgkmcnt(8)
	v_mfma_scale_f32_32x32x64_f8f6f4 v[98:113], v[222:229], v[130:137], v[98:113], v194, v193 op_sel_hi:[0,0,0]
	v_mov_b32_e32 v0, v219
	s_nop 1
	v_permlane32_swap_b32_e32 v219, v0
	v_add_f32_e32 v219, v219, v0
	v_fma_f32 v209, v209, v218, v219
	v_max_f32_e32 v177, v114, v115
	v_max3_f32 v177, v177, v116, v117
	v_max3_f32 v177, v177, v118, v119
	v_max3_f32 v177, v177, v120, v121
	v_max3_f32 v177, v177, v122, v123
	v_max3_f32 v177, v177, v124, v125
	v_max3_f32 v177, v177, v126, v127
	v_max3_f32 v177, v177, v128, v129
	s_waitcnt lgkmcnt(6)
	v_mfma_scale_f32_32x32x64_f8f6f4 v[50:65], v[246:253], v[90:97], v[50:65], v194, v194 op_sel_hi:[0,0,0]
	s_waitcnt lgkmcnt(4)
	v_mfma_scale_f32_32x32x64_f8f6f4 v[34:49], v[246:253], v[82:89], v[34:49], v194, v194 op_sel_hi:[0,0,0]
	s_waitcnt vmcnt(0)
	ds_write_b128 v210, v[158:161] offset:43008
	ds_write_b128 v211, v[162:165] offset:51200
	ds_write_b128 v212, v[154:157] offset:59392
	s_waitcnt lgkmcnt(5)
	v_mfma_scale_f32_32x32x64_f8f6f4 v[18:33], v[246:253], v[74:81], v[18:33], v194, v194 op_sel_hi:[0,0,0]
	s_waitcnt lgkmcnt(3)
	v_mfma_scale_f32_32x32x64_f8f6f4 v[2:17], v[246:253], v[66:73], v[2:17], v194, v194 op_sel_hi:[0,0,0]
	s_waitcnt lgkmcnt(0)
	s_barrier
	v_max_f32_e32 v0, v98, v99
	v_max3_f32 v0, v0, v100, v101
	v_max3_f32 v0, v0, v102, v103
	v_max3_f32 v0, v0, v104, v105
	v_max3_f32 v0, v0, v106, v107
	v_max3_f32 v0, v0, v108, v109
	v_max3_f32 v0, v0, v110, v111
	v_max3_f32 v0, v0, v112, v113
	v_max_f32_e32 v177, v177, v0
	v_mov_b32_e32 v0, v177
	v_mov_b32_e32 v221, 1.0
	s_nop 0
	v_permlane32_swap_b32_e32 v177, v0
	v_max_f32_e32 v177, v177, v0
	v_cmp_ge_f32_e32 vcc, s90, v177
	s_cmp_eq_u64 vcc, exec
	s_cbranch_scc0 .Lmla_h0_newmax
; __device__ __forceinline__ void finishSM9(f32x16& p0, f32x16& p1, float alpha, float& l_reg, v8i32& p8) {
; #pragma unroll
;   for (int r = 0; r < 16; ++r) { p0[r] = __builtin_amdgcn_exp2f(p0[r]); p1[r] = __builtin_amdgcn_exp2f(p1[r]); }
;   float ps = 0;
; #pragma unroll
;   for (int r = 0; r < 16; ++r) ps += p0[r];
; #pragma unroll
;   for (int r = 0; r < 16; ++r) ps += p1[r];
;   { auto rr = __builtin_amdgcn_permlane32_swap(__float_as_uint(ps), __float_as_uint(ps), false, false);
;     ps = __uint_as_float(rr[0]) + __uint_as_float(rr[1]); }
;   l_reg = l_reg * alpha + ps;
; #pragma unroll
;   for (int g = 0; g < 4; ++g) {
;     int w = __builtin_amdgcn_cvt_pk_fp8_f32(p0[4 * g], p0[4 * g + 1], 0, false); p8[g] = __builtin_amdgcn_cvt_pk_fp8_f32(p0[4 * g + 2], p0[4 * g + 3], w, true);
;     int u = __builtin_amdgcn_cvt_pk_fp8_f32(p1[4 * g], p1[4 * g + 1], 0, false); p8[4 + g] = __builtin_amdgcn_cvt_pk_fp8_f32(p1[4 * g + 2], p1[4 * g + 3], u, true); }
; }
; __device__ __forceinline__ void pv8(f32x16* o, const char* Vt, const v8i32 p8, int r32, int hi) {
;   const int sw = (r32 >> 2) & 3, a0 = r32 * 64 + (((hi * 2) ^ sw) << 4), a1 = r32 * 64 + (((hi * 2 + 1) ^ sw) << 4);
; #pragma unroll
;   for (int d0 = 0; d0 < 4; ++d0) {
;     const v8i32 vf = cat8(*reinterpret_cast<const v4i32*>(Vt + d0 * 2048 + a0), *reinterpret_cast<const v4i32*>(Vt + d0 * 2048 + a1));
;     o[d0] = __builtin_amdgcn_mfma_scale_f32_32x32x64_f8f6f4(p8, vf, o[d0], 0, 0, 0, 127, 0, 127); }
; }
; __device__ __forceinline__ void qkt9(f32x16& p0, f32x16& p1, const char* Kn, const char* Kr, const v8i32* qf, const float init, int r32, int hi) {
; #pragma unroll
;   for (int r = 0; r < 16; ++r) { p0[r] = init; p1[r] = init; }
; #pragma unroll
;   for (int s = 0; s < 2; ++s) { const int c0 = s * 4 + hi * 2;
;     const v8i32 a0 = cat8(*reinterpret_cast<const v4i32*>(Kn + KN8SW(r32, c0)), *reinterpret_cast<const v4i32*>(Kn + KN8SW(r32, c0 + 1)));
;     const v8i32 a1 = cat8(*reinterpret_cast<const v4i32*>(Kn + 4096 + KN8SW(r32, c0)), *reinterpret_cast<const v4i32*>(Kn + 4096 + KN8SW(r32, c0 + 1)));
;     p0 = __builtin_amdgcn_mfma_scale_f32_32x32x64_f8f6f4(a0, qf[s], p0, 0, 0, 0, 127, 0, 124);
;     p1 = __builtin_amdgcn_mfma_scale_f32_32x32x64_f8f6f4(a1, qf[s], p1, 0, 0, 0, 127, 0, 124); }
;   { const int c0 = hi * 2;
.Lmla_h0_cont:
	global_load_dwordx4 v[158:161], v176, s[18:19]
	global_load_dwordx4 v[162:165], v178, s[16:17]
	global_load_dwordx4 v[154:157], v[180:181], off
	ds_read_b128 v[82:85], v215 offset:51200
	ds_read_b128 v[86:89], v216 offset:51200
	ds_read_b128 v[222:225], v215 offset:55296
	ds_read_b128 v[226:229], v216 offset:55296
	v_add_u32_e32 v176, 0x2000, v176
	v_add_u32_e32 v178, 0x20000, v178
	s_mov_b64 s[20:21], 0x1000
	v_lshl_add_u64 v[180:181], v[180:181], 0, s[20:21]
	v_exp_f32_e32 v0, v114
	v_exp_f32_e32 v177, v115
	v_exp_f32_e32 v179, v116
	v_exp_f32_e32 v254, v117
	v_add_f32_e32 v219, v0, v177
	v_cvt_pk_fp8_f32 v246, v0, v177
	v_add_f32_e32 v219, v179, v219
	v_add_f32_e32 v219, v254, v219
	v_cvt_pk_fp8_f32 v246, v179, v254 op_sel:[0,0,1]
	s_waitcnt lgkmcnt(2)
	v_mfma_scale_f32_32x32x64_f8f6f4 v[82:97], v[82:89], v[146:153], v[230:245], v194, v193 op_sel_hi:[0,0,0]
	v_exp_f32_e32 v0, v118
	v_exp_f32_e32 v177, v119
	v_exp_f32_e32 v179, v120
	v_exp_f32_e32 v254, v121
	v_add_f32_e32 v219, v0, v219
	v_add_f32_e32 v219, v177, v219
	v_cvt_pk_fp8_f32 v247, v0, v177
	v_add_f32_e32 v219, v179, v219
	v_add_f32_e32 v219, v254, v219
	v_cvt_pk_fp8_f32 v247, v179, v254 op_sel:[0,0,1]
	ds_read_b128 v[114:117], v213 offset:51200
	ds_read_b128 v[118:121], v214 offset:51200
	s_waitcnt lgkmcnt(2)
	v_mfma_scale_f32_32x32x64_f8f6f4 v[66:81], v[222:229], v[146:153], v[230:245], v194, v193 op_sel_hi:[0,0,0]
	ds_read_b128 v[222:225], v213 offset:55296
	ds_read_b128 v[226:229], v214 offset:55296
	v_exp_f32_e32 v0, v122
	v_exp_f32_e32 v177, v123
	v_exp_f32_e32 v179, v124
	v_exp_f32_e32 v254, v125
	v_add_f32_e32 v219, v0, v219
	v_add_f32_e32 v219, v177, v219
	v_cvt_pk_fp8_f32 v248, v0, v177
	v_add_f32_e32 v219, v179, v219
	v_add_f32_e32 v219, v254, v219
	v_cvt_pk_fp8_f32 v248, v179, v254 op_sel:[0,0,1]
	v_exp_f32_e32 v0, v126
	v_exp_f32_e32 v177, v127
	v_exp_f32_e32 v179, v128
	v_exp_f32_e32 v254, v129
	v_add_f32_e32 v219, v0, v219
	v_add_f32_e32 v219, v177, v219
	v_cvt_pk_fp8_f32 v249, v0, v177
	v_add_f32_e32 v219, v179, v219
	v_add_f32_e32 v219, v254, v219
	v_cvt_pk_fp8_f32 v249, v179, v254 op_sel:[0,0,1]
	ds_read_b128 v[122:125], v185 offset:59392
	ds_read_b128 v[126:129], v186 offset:59392
	s_waitcnt lgkmcnt(4)
	v_mfma_scale_f32_32x32x64_f8f6f4 v[82:97], v[114:121], v[138:145], v[82:97], v194, v193 op_sel_hi:[0,0,0]
	v_exp_f32_e32 v0, v98
	v_exp_f32_e32 v177, v99
	v_exp_f32_e32 v179, v100
	v_exp_f32_e32 v254, v101
	v_add_f32_e32 v219, v0, v219
	v_add_f32_e32 v219, v177, v219
	v_cvt_pk_fp8_f32 v250, v0, v177
	v_add_f32_e32 v219, v179, v219
	v_add_f32_e32 v219, v254, v219
	v_cvt_pk_fp8_f32 v250, v179, v254 op_sel:[0,0,1]
	s_waitcnt lgkmcnt(2)
	v_mfma_scale_f32_32x32x64_f8f6f4 v[66:81], v[222:229], v[138:145], v[66:81], v194, v193 op_sel_hi:[0,0,0]
	ds_read_b128 v[222:225], v185 offset:61440
	ds_read_b128 v[226:229], v186 offset:61440
	v_exp_f32_e32 v0, v102
	v_exp_f32_e32 v177, v103
	v_exp_f32_e32 v179, v104
	v_exp_f32_e32 v254, v105
	v_add_f32_e32 v219, v0, v219
	v_add_f32_e32 v219, v177, v219
	v_cvt_pk_fp8_f32 v251, v0, v177
	v_add_f32_e32 v219, v179, v219
	v_add_f32_e32 v219, v254, v219
	v_cvt_pk_fp8_f32 v251, v179, v254 op_sel:[0,0,1]
	v_exp_f32_e32 v0, v106
	v_exp_f32_e32 v177, v107
	v_exp_f32_e32 v179, v108
	v_exp_f32_e32 v254, v109
	v_add_f32_e32 v219, v0, v219
	v_add_f32_e32 v219, v177, v219
	v_cvt_pk_fp8_f32 v252, v0, v177
	v_add_f32_e32 v219, v179, v219
	v_add_f32_e32 v219, v254, v219
	v_cvt_pk_fp8_f32 v252, v179, v254 op_sel:[0,0,1]
	s_waitcnt lgkmcnt(2)
	v_mfma_scale_f32_32x32x64_f8f6f4 v[82:97], v[122:129], v[130:137], v[82:97], v194, v193 op_sel_hi:[0,0,0]
	v_exp_f32_e32 v0, v110
	v_exp_f32_e32 v177, v111
	v_exp_f32_e32 v179, v112
	v_exp_f32_e32 v254, v113
	v_add_f32_e32 v219, v0, v219
	v_add_f32_e32 v219, v177, v219
	v_cvt_pk_fp8_f32 v253, v0, v177
	v_add_f32_e32 v219, v179, v219
	v_add_f32_e32 v219, v254, v219
	v_cvt_pk_fp8_f32 v253, v179, v254 op_sel:[0,0,1]
	ds_read_b128 v[122:125], v185 offset:8192
	ds_read_b128 v[126:129], v186 offset:8192
	ds_read_b128 v[114:117], v185 offset:10240
	ds_read_b128 v[118:121], v186 offset:10240
	ds_read_b128 v[106:109], v185 offset:12288
	ds_read_b128 v[110:113], v186 offset:12288
	ds_read_b128 v[98:101], v185 offset:14336
	ds_read_b128 v[102:105], v186 offset:14336
	s_waitcnt lgkmcnt(8)
	v_mfma_scale_f32_32x32x64_f8f6f4 v[66:81], v[222:229], v[130:137], v[66:81], v194, v193 op_sel_hi:[0,0,0]
	v_mov_b32_e32 v0, v219
	s_nop 1
	v_permlane32_swap_b32_e32 v219, v0
	v_add_f32_e32 v219, v219, v0
	v_fma_f32 v209, v209, v221, v219
	v_max_f32_e32 v177, v82, v83
	v_max3_f32 v177, v177, v84, v85
	v_max3_f32 v177, v177, v86, v87
	v_max3_f32 v177, v177, v88, v89
	v_max3_f32 v177, v177, v90, v91
	v_max3_f32 v177, v177, v92, v93
	v_max3_f32 v177, v177, v94, v95
	v_max3_f32 v177, v177, v96, v97
	s_waitcnt lgkmcnt(6)
	v_mfma_scale_f32_32x32x64_f8f6f4 v[50:65], v[246:253], v[122:129], v[50:65], v194, v194 op_sel_hi:[0,0,0]
	s_waitcnt lgkmcnt(4)
	v_mfma_scale_f32_32x32x64_f8f6f4 v[34:49], v[246:253], v[114:121], v[34:49], v194, v194 op_sel_hi:[0,0,0]
	s_waitcnt vmcnt(0)
	ds_write_b128 v210, v[158:161]
	ds_write_b128 v211, v[162:165] offset:16384
	ds_write_b128 v212, v[154:157] offset:32768
	s_waitcnt lgkmcnt(5)
	v_mfma_scale_f32_32x32x64_f8f6f4 v[18:33], v[246:253], v[106:113], v[18:33], v194, v194 op_sel_hi:[0,0,0]
	s_waitcnt lgkmcnt(3)
	v_mfma_scale_f32_32x32x64_f8f6f4 v[2:17], v[246:253], v[98:105], v[2:17], v194, v194 op_sel_hi:[0,0,0]
	s_waitcnt lgkmcnt(0)
	s_barrier
	v_max_f32_e32 v0, v66, v67
	v_max3_f32 v0, v0, v68, v69
	v_max3_f32 v0, v0, v70, v71
	v_max3_f32 v0, v0, v72, v73
	v_max3_f32 v0, v0, v74, v75
	v_max3_f32 v0, v0, v76, v77
	v_max3_f32 v0, v0, v78, v79
	v_max3_f32 v0, v0, v80, v81
	v_max_f32_e32 v177, v177, v0
	v_mov_b32_e32 v0, v177
	v_mov_b32_e32 v218, 1.0
	s_nop 0
	v_permlane32_swap_b32_e32 v177, v0
	v_max_f32_e32 v177, v177, v0
	v_cmp_ge_f32_e32 vcc, s90, v177
	s_cmp_eq_u64 vcc, exec
	s_cbranch_scc0 .Lmla_h1_newmax
; __device__ __forceinline__ void finishSM9(f32x16& p0, f32x16& p1, float alpha, float& l_reg, v8i32& p8) {
; #pragma unroll
;   for (int r = 0; r < 16; ++r) { p0[r] = __builtin_amdgcn_exp2f(p0[r]); p1[r] = __builtin_amdgcn_exp2f(p1[r]); }
;   float ps = 0;
; #pragma unroll
;   for (int r = 0; r < 16; ++r) ps += p0[r];
; #pragma unroll
;   for (int r = 0; r < 16; ++r) ps += p1[r];
;   { auto rr = __builtin_amdgcn_permlane32_swap(__float_as_uint(ps), __float_as_uint(ps), false, false);
;     ps = __uint_as_float(rr[0]) + __uint_as_float(rr[1]); }
;   l_reg = l_reg * alpha + ps;
; #pragma unroll
;   for (int g = 0; g < 4; ++g) {
;     int w = __builtin_amdgcn_cvt_pk_fp8_f32(p0[4 * g], p0[4 * g + 1], 0, false); p8[g] = __builtin_amdgcn_cvt_pk_fp8_f32(p0[4 * g + 2], p0[4 * g + 3], w, true);
;     int u = __builtin_amdgcn_cvt_pk_fp8_f32(p1[4 * g], p1[4 * g + 1], 0, false); p8[4 + g] = __builtin_amdgcn_cvt_pk_fp8_f32(p1[4 * g + 2], p1[4 * g + 3], u, true); }
; }
; __device__ __forceinline__ void pv8(f32x16* o, const char* Vt, const v8i32 p8, int r32, int hi) {
;   const int sw = (r32 >> 2) & 3, a0 = r32 * 64 + (((hi * 2) ^ sw) << 4), a1 = r32 * 64 + (((hi * 2 + 1) ^ sw) << 4);
; #pragma unroll
;   for (int d0 = 0; d0 < 4; ++d0) {
;     const v8i32 vf = cat8(*reinterpret_cast<const v4i32*>(Vt + d0 * 2048 + a0), *reinterpret_cast<const v4i32*>(Vt + d0 * 2048 + a1));
;     o[d0] = __builtin_amdgcn_mfma_scale_f32_32x32x64_f8f6f4(p8, vf, o[d0], 0, 0, 0, 127, 0, 127); }
; }
; __device__ __forceinline__ void qkt9(f32x16& p0, f32x16& p1, const char* Kn, const char* Kr, const v8i32* qf, const float init, int r32, int hi) {
; #pragma unroll
;   for (int r = 0; r < 16; ++r) { p0[r] = init; p1[r] = init; }
; #pragma unroll
;   for (int s = 0; s < 2; ++s) { const int c0 = s * 4 + hi * 2;
;     const v8i32 a0 = cat8(*reinterpret_cast<const v4i32*>(Kn + KN8SW(r32, c0)), *reinterpret_cast<const v4i32*>(Kn + KN8SW(r32, c0 + 1)));
;     const v8i32 a1 = cat8(*reinterpret_cast<const v4i32*>(Kn + 4096 + KN8SW(r32, c0)), *reinterpret_cast<const v4i32*>(Kn + 4096 + KN8SW(r32, c0 + 1)));
;     p0 = __builtin_amdgcn_mfma_scale_f32_32x32x64_f8f6f4(a0, qf[s], p0, 0, 0, 0, 127, 0, 124);
;     p1 = __builtin_amdgcn_mfma_scale_f32_32x32x64_f8f6f4(a1, qf[s], p1, 0, 0, 0, 127, 0, 124); }
;   { const int c0 = hi * 2;
.Lmla_h1_cont:
	global_load_dwordx4 v[158:161], v176, s[18:19]
	global_load_dwordx4 v[162:165], v178, s[16:17]
	global_load_dwordx4 v[154:157], v[180:181], off
	ds_read_b128 v[114:117], v215 offset:16384
	ds_read_b128 v[118:121], v216 offset:16384
	ds_read_b128 v[222:225], v215 offset:20480
	ds_read_b128 v[226:229], v216 offset:20480
	v_add_u32_e32 v176, 0x2000, v176
	v_add_u32_e32 v178, 0x20000, v178
	s_mov_b64 s[20:21], 0x1000
	v_lshl_add_u64 v[180:181], v[180:181], 0, s[20:21]
	v_exp_f32_e32 v0, v82
	v_exp_f32_e32 v177, v83
	v_exp_f32_e32 v179, v84
	v_exp_f32_e32 v254, v85
	v_add_f32_e32 v219, v0, v177
	v_cvt_pk_fp8_f32 v246, v0, v177
	v_add_f32_e32 v219, v179, v219
	v_add_f32_e32 v219, v254, v219
	v_cvt_pk_fp8_f32 v246, v179, v254 op_sel:[0,0,1]
	s_waitcnt lgkmcnt(2)
	v_mfma_scale_f32_32x32x64_f8f6f4 v[114:129], v[114:121], v[146:153], v[230:245], v194, v193 op_sel_hi:[0,0,0]
	v_exp_f32_e32 v0, v86
	v_exp_f32_e32 v177, v87
	v_exp_f32_e32 v179, v88
	v_exp_f32_e32 v254, v89
	v_add_f32_e32 v219, v0, v219
	v_add_f32_e32 v219, v177, v219
	v_cvt_pk_fp8_f32 v247, v0, v177
	v_add_f32_e32 v219, v179, v219
	v_add_f32_e32 v219, v254, v219
	v_cvt_pk_fp8_f32 v247, v179, v254 op_sel:[0,0,1]
	ds_read_b128 v[82:85], v213 offset:16384
	ds_read_b128 v[86:89], v214 offset:16384
	s_waitcnt lgkmcnt(2)
	v_mfma_scale_f32_32x32x64_f8f6f4 v[98:113], v[222:229], v[146:153], v[230:245], v194, v193 op_sel_hi:[0,0,0]
	ds_read_b128 v[222:225], v213 offset:20480
	ds_read_b128 v[226:229], v214 offset:20480
	v_exp_f32_e32 v0, v90
	v_exp_f32_e32 v177, v91
	v_exp_f32_e32 v179, v92
	v_exp_f32_e32 v254, v93
	v_add_f32_e32 v219, v0, v219
	v_add_f32_e32 v219, v177, v219
	v_cvt_pk_fp8_f32 v248, v0, v177
	v_add_f32_e32 v219, v179, v219
	v_add_f32_e32 v219, v254, v219
	v_cvt_pk_fp8_f32 v248, v179, v254 op_sel:[0,0,1]
	v_exp_f32_e32 v0, v94
	v_exp_f32_e32 v177, v95
	v_exp_f32_e32 v179, v96
	v_exp_f32_e32 v254, v97
	v_add_f32_e32 v219, v0, v219
	v_add_f32_e32 v219, v177, v219
	v_cvt_pk_fp8_f32 v249, v0, v177
	v_add_f32_e32 v219, v179, v219
	v_add_f32_e32 v219, v254, v219
	v_cvt_pk_fp8_f32 v249, v179, v254 op_sel:[0,0,1]
	ds_read_b128 v[90:93], v185 offset:32768
	ds_read_b128 v[94:97], v186 offset:32768
	s_waitcnt lgkmcnt(4)
	v_mfma_scale_f32_32x32x64_f8f6f4 v[114:129], v[82:89], v[138:145], v[114:129], v194, v193 op_sel_hi:[0,0,0]
	v_exp_f32_e32 v0, v66
	v_exp_f32_e32 v177, v67
	v_exp_f32_e32 v179, v68
	v_exp_f32_e32 v254, v69
	v_add_f32_e32 v219, v0, v219
	v_add_f32_e32 v219, v177, v219
	v_cvt_pk_fp8_f32 v250, v0, v177
	v_add_f32_e32 v219, v179, v219
	v_add_f32_e32 v219, v254, v219
	v_cvt_pk_fp8_f32 v250, v179, v254 op_sel:[0,0,1]
	s_waitcnt lgkmcnt(2)
	v_mfma_scale_f32_32x32x64_f8f6f4 v[98:113], v[222:229], v[138:145], v[98:113], v194, v193 op_sel_hi:[0,0,0]
	ds_read_b128 v[222:225], v185 offset:34816
	ds_read_b128 v[226:229], v186 offset:34816
	v_exp_f32_e32 v0, v70
	v_exp_f32_e32 v177, v71
	v_exp_f32_e32 v179, v72
	v_exp_f32_e32 v254, v73
	v_add_f32_e32 v219, v0, v219
	v_add_f32_e32 v219, v177, v219
	v_cvt_pk_fp8_f32 v251, v0, v177
	v_add_f32_e32 v219, v179, v219
	v_add_f32_e32 v219, v254, v219
	v_cvt_pk_fp8_f32 v251, v179, v254 op_sel:[0,0,1]
	v_exp_f32_e32 v0, v74
	v_exp_f32_e32 v177, v75
	v_exp_f32_e32 v179, v76
	v_exp_f32_e32 v254, v77
	v_add_f32_e32 v219, v0, v219
	v_add_f32_e32 v219, v177, v219
	v_cvt_pk_fp8_f32 v252, v0, v177
	v_add_f32_e32 v219, v179, v219
	v_add_f32_e32 v219, v254, v219
	v_cvt_pk_fp8_f32 v252, v179, v254 op_sel:[0,0,1]
	s_waitcnt lgkmcnt(2)
	v_mfma_scale_f32_32x32x64_f8f6f4 v[114:129], v[90:97], v[130:137], v[114:129], v194, v193 op_sel_hi:[0,0,0]
	v_exp_f32_e32 v0, v78
	v_exp_f32_e32 v177, v79
	v_exp_f32_e32 v179, v80
	v_exp_f32_e32 v254, v81
	v_add_f32_e32 v219, v0, v219
	v_add_f32_e32 v219, v177, v219
	v_cvt_pk_fp8_f32 v253, v0, v177
	v_add_f32_e32 v219, v179, v219
	v_add_f32_e32 v219, v254, v219
	v_cvt_pk_fp8_f32 v253, v179, v254 op_sel:[0,0,1]
	ds_read_b128 v[90:93], v185 offset:43008
	ds_read_b128 v[94:97], v186 offset:43008
	ds_read_b128 v[82:85], v185 offset:45056
	ds_read_b128 v[86:89], v186 offset:45056
	ds_read_b128 v[74:77], v185 offset:47104
	ds_read_b128 v[78:81], v186 offset:47104
	ds_read_b128 v[66:69], v185 offset:49152
	ds_read_b128 v[70:73], v186 offset:49152
	s_waitcnt lgkmcnt(8)
	v_mfma_scale_f32_32x32x64_f8f6f4 v[98:113], v[222:229], v[130:137], v[98:113], v194, v193 op_sel_hi:[0,0,0]
	v_mov_b32_e32 v0, v219
	s_nop 1
	v_permlane32_swap_b32_e32 v219, v0
	v_add_f32_e32 v219, v219, v0
	v_fma_f32 v209, v209, v218, v219
	v_max_f32_e32 v177, v114, v115
	v_max3_f32 v177, v177, v116, v117
	v_max3_f32 v177, v177, v118, v119
	v_max3_f32 v177, v177, v120, v121
	v_max3_f32 v177, v177, v122, v123
	v_max3_f32 v177, v177, v124, v125
	v_max3_f32 v177, v177, v126, v127
	v_max3_f32 v177, v177, v128, v129
	s_waitcnt lgkmcnt(6)
	v_mfma_scale_f32_32x32x64_f8f6f4 v[50:65], v[246:253], v[90:97], v[50:65], v194, v194 op_sel_hi:[0,0,0]
	s_waitcnt lgkmcnt(4)
	v_mfma_scale_f32_32x32x64_f8f6f4 v[34:49], v[246:253], v[82:89], v[34:49], v194, v194 op_sel_hi:[0,0,0]
	s_waitcnt vmcnt(0)
	ds_write_b128 v210, v[158:161] offset:8192
	ds_write_b128 v211, v[162:165] offset:24576
	ds_write_b128 v212, v[154:157] offset:36864
	s_waitcnt lgkmcnt(5)
	v_mfma_scale_f32_32x32x64_f8f6f4 v[18:33], v[246:253], v[74:81], v[18:33], v194, v194 op_sel_hi:[0,0,0]
	s_waitcnt lgkmcnt(3)
	v_mfma_scale_f32_32x32x64_f8f6f4 v[2:17], v[246:253], v[66:73], v[2:17], v194, v194 op_sel_hi:[0,0,0]
	s_waitcnt lgkmcnt(0)
	s_barrier
	v_max_f32_e32 v0, v98, v99
	v_max3_f32 v0, v0, v100, v101
	v_max3_f32 v0, v0, v102, v103
	v_max3_f32 v0, v0, v104, v105
	v_max3_f32 v0, v0, v106, v107
	v_max3_f32 v0, v0, v108, v109
	v_max3_f32 v0, v0, v110, v111
	v_max3_f32 v0, v0, v112, v113
	v_max_f32_e32 v177, v177, v0
	v_mov_b32_e32 v0, v177
	v_mov_b32_e32 v221, 1.0
	s_nop 0
	v_permlane32_swap_b32_e32 v177, v0
	v_max_f32_e32 v177, v177, v0
	v_cmp_ge_f32_e32 vcc, s90, v177
	s_cmp_eq_u64 vcc, exec
	s_cbranch_scc0 .Lmla_h2_newmax
; __device__ __forceinline__ void finishSM9(f32x16& p0, f32x16& p1, float alpha, float& l_reg, v8i32& p8) {
; #pragma unroll
;   for (int r = 0; r < 16; ++r) { p0[r] = __builtin_amdgcn_exp2f(p0[r]); p1[r] = __builtin_amdgcn_exp2f(p1[r]); }
;   float ps = 0;
; #pragma unroll
;   for (int r = 0; r < 16; ++r) ps += p0[r];
; #pragma unroll
;   for (int r = 0; r < 16; ++r) ps += p1[r];
;   { auto rr = __builtin_amdgcn_permlane32_swap(__float_as_uint(ps), __float_as_uint(ps), false, false);
;     ps = __uint_as_float(rr[0]) + __uint_as_float(rr[1]); }
;   l_reg = l_reg * alpha + ps;
; #pragma unroll
;   for (int g = 0; g < 4; ++g) {
;     int w = __builtin_amdgcn_cvt_pk_fp8_f32(p0[4 * g], p0[4 * g + 1], 0, false); p8[g] = __builtin_amdgcn_cvt_pk_fp8_f32(p0[4 * g + 2], p0[4 * g + 3], w, true);
;     int u = __builtin_amdgcn_cvt_pk_fp8_f32(p1[4 * g], p1[4 * g + 1], 0, false); p8[4 + g] = __builtin_amdgcn_cvt_pk_fp8_f32(p1[4 * g + 2], p1[4 * g + 3], u, true); }
; }
; __device__ __forceinline__ void pv8(f32x16* o, const char* Vt, const v8i32 p8, int r32, int hi) {
;   const int sw = (r32 >> 2) & 3, a0 = r32 * 64 + (((hi * 2) ^ sw) << 4), a1 = r32 * 64 + (((hi * 2 + 1) ^ sw) << 4);
; #pragma unroll
;   for (int d0 = 0; d0 < 4; ++d0) {
;     const v8i32 vf = cat8(*reinterpret_cast<const v4i32*>(Vt + d0 * 2048 + a0), *reinterpret_cast<const v4i32*>(Vt + d0 * 2048 + a1));
;     o[d0] = __builtin_amdgcn_mfma_scale_f32_32x32x64_f8f6f4(p8, vf, o[d0], 0, 0, 0, 127, 0, 127); }
; }
; __device__ __forceinline__ void qkt9(f32x16& p0, f32x16& p1, const char* Kn, const char* Kr, const v8i32* qf, const float init, int r32, int hi) {
; #pragma unroll
;   for (int r = 0; r < 16; ++r) { p0[r] = init; p1[r] = init; }
; #pragma unroll
;   for (int s = 0; s < 2; ++s) { const int c0 = s * 4 + hi * 2;
;     const v8i32 a0 = cat8(*reinterpret_cast<const v4i32*>(Kn + KN8SW(r32, c0)), *reinterpret_cast<const v4i32*>(Kn + KN8SW(r32, c0 + 1)));
;     const v8i32 a1 = cat8(*reinterpret_cast<const v4i32*>(Kn + 4096 + KN8SW(r32, c0)), *reinterpret_cast<const v4i32*>(Kn + 4096 + KN8SW(r32, c0 + 1)));
;     p0 = __builtin_amdgcn_mfma_scale_f32_32x32x64_f8f6f4(a0, qf[s], p0, 0, 0, 0, 127, 0, 124);
;     p1 = __builtin_amdgcn_mfma_scale_f32_32x32x64_f8f6f4(a1, qf[s], p1, 0, 0, 0, 127, 0, 124); }
;   { const int c0 = hi * 2;
.Lmla_h2_cont:
	global_load_dwordx4 v[158:161], v176, s[18:19]
	global_load_dwordx4 v[162:165], v178, s[16:17]
	global_load_dwordx4 v[154:157], v[180:181], off
	ds_read_b128 v[82:85], v215 offset:24576
	ds_read_b128 v[86:89], v216 offset:24576
	ds_read_b128 v[222:225], v215 offset:28672
	ds_read_b128 v[226:229], v216 offset:28672
	v_add_u32_e32 v176, 0x2000, v176
	v_add_u32_e32 v178, 0x20000, v178
	s_mov_b64 s[20:21], 0x1000
	v_lshl_add_u64 v[180:181], v[180:181], 0, s[20:21]
	v_exp_f32_e32 v0, v114
	v_exp_f32_e32 v177, v115
	v_exp_f32_e32 v179, v116
	v_exp_f32_e32 v254, v117
	v_add_f32_e32 v219, v0, v177
	v_cvt_pk_fp8_f32 v246, v0, v177
	v_add_f32_e32 v219, v179, v219
	v_add_f32_e32 v219, v254, v219
	v_cvt_pk_fp8_f32 v246, v179, v254 op_sel:[0,0,1]
	s_waitcnt lgkmcnt(2)
	v_mfma_scale_f32_32x32x64_f8f6f4 v[82:97], v[82:89], v[146:153], v[230:245], v194, v193 op_sel_hi:[0,0,0]
	v_exp_f32_e32 v0, v118
	v_exp_f32_e32 v177, v119
	v_exp_f32_e32 v179, v120
	v_exp_f32_e32 v254, v121
	v_add_f32_e32 v219, v0, v219
	v_add_f32_e32 v219, v177, v219
	v_cvt_pk_fp8_f32 v247, v0, v177
	v_add_f32_e32 v219, v179, v219
	v_add_f32_e32 v219, v254, v219
	v_cvt_pk_fp8_f32 v247, v179, v254 op_sel:[0,0,1]
	ds_read_b128 v[114:117], v213 offset:24576
	ds_read_b128 v[118:121], v214 offset:24576
	s_waitcnt lgkmcnt(2)
	v_mfma_scale_f32_32x32x64_f8f6f4 v[66:81], v[222:229], v[146:153], v[230:245], v194, v193 op_sel_hi:[0,0,0]
	ds_read_b128 v[222:225], v213 offset:28672
	ds_read_b128 v[226:229], v214 offset:28672
	v_exp_f32_e32 v0, v122
	v_exp_f32_e32 v177, v123
	v_exp_f32_e32 v179, v124
	v_exp_f32_e32 v254, v125
	v_add_f32_e32 v219, v0, v219
	v_add_f32_e32 v219, v177, v219
	v_cvt_pk_fp8_f32 v248, v0, v177
	v_add_f32_e32 v219, v179, v219
	v_add_f32_e32 v219, v254, v219
	v_cvt_pk_fp8_f32 v248, v179, v254 op_sel:[0,0,1]
	v_exp_f32_e32 v0, v126
	v_exp_f32_e32 v177, v127
	v_exp_f32_e32 v179, v128
	v_exp_f32_e32 v254, v129
	v_add_f32_e32 v219, v0, v219
	v_add_f32_e32 v219, v177, v219
	v_cvt_pk_fp8_f32 v249, v0, v177
	v_add_f32_e32 v219, v179, v219
	v_add_f32_e32 v219, v254, v219
	v_cvt_pk_fp8_f32 v249, v179, v254 op_sel:[0,0,1]
	ds_read_b128 v[122:125], v185 offset:36864
	ds_read_b128 v[126:129], v186 offset:36864
	s_waitcnt lgkmcnt(4)
	v_mfma_scale_f32_32x32x64_f8f6f4 v[82:97], v[114:121], v[138:145], v[82:97], v194, v193 op_sel_hi:[0,0,0]
	v_exp_f32_e32 v0, v98
	v_exp_f32_e32 v177, v99
	v_exp_f32_e32 v179, v100
	v_exp_f32_e32 v254, v101
	v_add_f32_e32 v219, v0, v219
	v_add_f32_e32 v219, v177, v219
	v_cvt_pk_fp8_f32 v250, v0, v177
	v_add_f32_e32 v219, v179, v219
	v_add_f32_e32 v219, v254, v219
	v_cvt_pk_fp8_f32 v250, v179, v254 op_sel:[0,0,1]
	s_waitcnt lgkmcnt(2)
	v_mfma_scale_f32_32x32x64_f8f6f4 v[66:81], v[222:229], v[138:145], v[66:81], v194, v193 op_sel_hi:[0,0,0]
	ds_read_b128 v[222:225], v185 offset:38912
	ds_read_b128 v[226:229], v186 offset:38912
	v_exp_f32_e32 v0, v102
	v_exp_f32_e32 v177, v103
	v_exp_f32_e32 v179, v104
	v_exp_f32_e32 v254, v105
	v_add_f32_e32 v219, v0, v219
	v_add_f32_e32 v219, v177, v219
	v_cvt_pk_fp8_f32 v251, v0, v177
	v_add_f32_e32 v219, v179, v219
	v_add_f32_e32 v219, v254, v219
	v_cvt_pk_fp8_f32 v251, v179, v254 op_sel:[0,0,1]
	v_exp_f32_e32 v0, v106
	v_exp_f32_e32 v177, v107
	v_exp_f32_e32 v179, v108
	v_exp_f32_e32 v254, v109
	v_add_f32_e32 v219, v0, v219
	v_add_f32_e32 v219, v177, v219
	v_cvt_pk_fp8_f32 v252, v0, v177
	v_add_f32_e32 v219, v179, v219
	v_add_f32_e32 v219, v254, v219
	v_cvt_pk_fp8_f32 v252, v179, v254 op_sel:[0,0,1]
	s_waitcnt lgkmcnt(2)
	v_mfma_scale_f32_32x32x64_f8f6f4 v[82:97], v[122:129], v[130:137], v[82:97], v194, v193 op_sel_hi:[0,0,0]
	v_exp_f32_e32 v0, v110
	v_exp_f32_e32 v177, v111
	v_exp_f32_e32 v179, v112
	v_exp_f32_e32 v254, v113
	v_add_f32_e32 v219, v0, v219
	v_add_f32_e32 v219, v177, v219
	v_cvt_pk_fp8_f32 v253, v0, v177
	v_add_f32_e32 v219, v179, v219
	v_add_f32_e32 v219, v254, v219
	v_cvt_pk_fp8_f32 v253, v179, v254 op_sel:[0,0,1]
	ds_read_b128 v[122:125], v185 offset:0
	ds_read_b128 v[126:129], v186 offset:0
	ds_read_b128 v[114:117], v185 offset:2048
	ds_read_b128 v[118:121], v186 offset:2048
	ds_read_b128 v[106:109], v185 offset:4096
	ds_read_b128 v[110:113], v186 offset:4096
	ds_read_b128 v[98:101], v185 offset:6144
	ds_read_b128 v[102:105], v186 offset:6144
	s_waitcnt lgkmcnt(8)
	v_mfma_scale_f32_32x32x64_f8f6f4 v[66:81], v[222:229], v[130:137], v[66:81], v194, v193 op_sel_hi:[0,0,0]
	v_mov_b32_e32 v0, v219
	s_nop 1
	v_permlane32_swap_b32_e32 v219, v0
	v_add_f32_e32 v219, v219, v0
	v_fma_f32 v209, v209, v221, v219
	v_max_f32_e32 v177, v82, v83
	v_max3_f32 v177, v177, v84, v85
	v_max3_f32 v177, v177, v86, v87
	v_max3_f32 v177, v177, v88, v89
	v_max3_f32 v177, v177, v90, v91
	v_max3_f32 v177, v177, v92, v93
	v_max3_f32 v177, v177, v94, v95
	v_max3_f32 v177, v177, v96, v97
	s_waitcnt lgkmcnt(6)
	v_mfma_scale_f32_32x32x64_f8f6f4 v[50:65], v[246:253], v[122:129], v[50:65], v194, v194 op_sel_hi:[0,0,0]
	s_waitcnt lgkmcnt(4)
	v_mfma_scale_f32_32x32x64_f8f6f4 v[34:49], v[246:253], v[114:121], v[34:49], v194, v194 op_sel_hi:[0,0,0]
	s_waitcnt vmcnt(0)
	ds_write_b128 v210, v[158:161] offset:43008
	ds_write_b128 v211, v[162:165] offset:51200
	ds_write_b128 v212, v[154:157] offset:59392
	s_waitcnt lgkmcnt(5)
	v_mfma_scale_f32_32x32x64_f8f6f4 v[18:33], v[246:253], v[106:113], v[18:33], v194, v194 op_sel_hi:[0,0,0]
	s_waitcnt lgkmcnt(3)
	v_mfma_scale_f32_32x32x64_f8f6f4 v[2:17], v[246:253], v[98:105], v[2:17], v194, v194 op_sel_hi:[0,0,0]
	s_waitcnt lgkmcnt(0)
	s_barrier
	v_max_f32_e32 v0, v66, v67
	v_max3_f32 v0, v0, v68, v69
	v_max3_f32 v0, v0, v70, v71
	v_max3_f32 v0, v0, v72, v73
	v_max3_f32 v0, v0, v74, v75
	v_max3_f32 v0, v0, v76, v77
	v_max3_f32 v0, v0, v78, v79
	v_max3_f32 v0, v0, v80, v81
	v_max_f32_e32 v177, v177, v0
	v_mov_b32_e32 v0, v177
	v_mov_b32_e32 v218, 1.0
	s_nop 0
	v_permlane32_swap_b32_e32 v177, v0
	v_max_f32_e32 v177, v177, v0
	v_cmp_ge_f32_e32 vcc, s90, v177
	s_cmp_eq_u64 vcc, exec
	s_cbranch_scc0 .Lmla_h3_newmax
; __device__ __forceinline__ void finishSM9(f32x16& p0, f32x16& p1, float alpha, float& l_reg, v8i32& p8) {
; #pragma unroll
;   for (int r = 0; r < 16; ++r) { p0[r] = __builtin_amdgcn_exp2f(p0[r]); p1[r] = __builtin_amdgcn_exp2f(p1[r]); }
;   float ps = 0;
; #pragma unroll
;   for (int r = 0; r < 16; ++r) ps += p0[r];
; #pragma unroll
;   for (int r = 0; r < 16; ++r) ps += p1[r];
;   { auto rr = __builtin_amdgcn_permlane32_swap(__float_as_uint(ps), __float_as_uint(ps), false, false);
;     ps = __uint_as_float(rr[0]) + __uint_as_float(rr[1]); }
;   l_reg = l_reg * alpha + ps;
; #pragma unroll
;   for (int g = 0; g < 4; ++g) {
;     int w = __builtin_amdgcn_cvt_pk_fp8_f32(p0[4 * g], p0[4 * g + 1], 0, false); p8[g] = __builtin_amdgcn_cvt_pk_fp8_f32(p0[4 * g + 2], p0[4 * g + 3], w, true);
;     int u = __builtin_amdgcn_cvt_pk_fp8_f32(p1[4 * g], p1[4 * g + 1], 0, false); p8[4 + g] = __builtin_amdgcn_cvt_pk_fp8_f32(p1[4 * g + 2], p1[4 * g + 3], u, true); }
; }
; __device__ __forceinline__ void pv8(f32x16* o, const char* Vt, const v8i32 p8, int r32, int hi) {
;   const int sw = (r32 >> 2) & 3, a0 = r32 * 64 + (((hi * 2) ^ sw) << 4), a1 = r32 * 64 + (((hi * 2 + 1) ^ sw) << 4);
; #pragma unroll
;   for (int d0 = 0; d0 < 4; ++d0) {
;     const v8i32 vf = cat8(*reinterpret_cast<const v4i32*>(Vt + d0 * 2048 + a0), *reinterpret_cast<const v4i32*>(Vt + d0 * 2048 + a1));
;     o[d0] = __builtin_amdgcn_mfma_scale_f32_32x32x64_f8f6f4(p8, vf, o[d0], 0, 0, 0, 127, 0, 127); }
; }
; __device__ __forceinline__ void qkt9(f32x16& p0, f32x16& p1, const char* Kn, const char* Kr, const v8i32* qf, const float init, int r32, int hi) {
; #pragma unroll
;   for (int r = 0; r < 16; ++r) { p0[r] = init; p1[r] = init; }
; #pragma unroll
;   for (int s = 0; s < 2; ++s) { const int c0 = s * 4 + hi * 2;
;     const v8i32 a0 = cat8(*reinterpret_cast<const v4i32*>(Kn + KN8SW(r32, c0)), *reinterpret_cast<const v4i32*>(Kn + KN8SW(r32, c0 + 1)));
;     const v8i32 a1 = cat8(*reinterpret_cast<const v4i32*>(Kn + 4096 + KN8SW(r32, c0)), *reinterpret_cast<const v4i32*>(Kn + 4096 + KN8SW(r32, c0 + 1)));
;     p0 = __builtin_amdgcn_mfma_scale_f32_32x32x64_f8f6f4(a0, qf[s], p0, 0, 0, 0, 127, 0, 124);
;     p1 = __builtin_amdgcn_mfma_scale_f32_32x32x64_f8f6f4(a1, qf[s], p1, 0, 0, 0, 127, 0, 124); }
;   { const int c0 = hi * 2;
.Lmla_h3_cont:
	global_load_dwordx4 v[158:161], v176, s[18:19]
	global_load_dwordx4 v[162:165], v178, s[16:17]
	global_load_dwordx4 v[154:157], v[180:181], off
	ds_read_b128 v[114:117], v215 offset:51200
	ds_read_b128 v[118:121], v216 offset:51200
	ds_read_b128 v[222:225], v215 offset:55296
	ds_read_b128 v[226:229], v216 offset:55296
	v_add_u32_e32 v176, 0x2000, v176
	v_add_u32_e32 v178, 0x20000, v178
	s_mov_b64 s[20:21], 0x1000
	v_lshl_add_u64 v[180:181], v[180:181], 0, s[20:21]
	v_exp_f32_e32 v0, v82
	v_exp_f32_e32 v177, v83
	v_exp_f32_e32 v179, v84
	v_exp_f32_e32 v254, v85
	v_add_f32_e32 v219, v0, v177
	v_cvt_pk_fp8_f32 v246, v0, v177
	v_add_f32_e32 v219, v179, v219
	v_add_f32_e32 v219, v254, v219
	v_cvt_pk_fp8_f32 v246, v179, v254 op_sel:[0,0,1]
	s_waitcnt lgkmcnt(2)
	v_mfma_scale_f32_32x32x64_f8f6f4 v[114:129], v[114:121], v[146:153], v[230:245], v194, v193 op_sel_hi:[0,0,0]
	v_exp_f32_e32 v0, v86
	v_exp_f32_e32 v177, v87
	v_exp_f32_e32 v179, v88
	v_exp_f32_e32 v254, v89
	v_add_f32_e32 v219, v0, v219
	v_add_f32_e32 v219, v177, v219
	v_cvt_pk_fp8_f32 v247, v0, v177
	v_add_f32_e32 v219, v179, v219
	v_add_f32_e32 v219, v254, v219
	v_cvt_pk_fp8_f32 v247, v179, v254 op_sel:[0,0,1]
	ds_read_b128 v[82:85], v213 offset:51200
	ds_read_b128 v[86:89], v214 offset:51200
	s_waitcnt lgkmcnt(2)
	v_mfma_scale_f32_32x32x64_f8f6f4 v[98:113], v[222:229], v[146:153], v[230:245], v194, v193 op_sel_hi:[0,0,0]
	ds_read_b128 v[222:225], v213 offset:55296
	ds_read_b128 v[226:229], v214 offset:55296
	v_exp_f32_e32 v0, v90
	v_exp_f32_e32 v177, v91
	v_exp_f32_e32 v179, v92
	v_exp_f32_e32 v254, v93
	v_add_f32_e32 v219, v0, v219
	v_add_f32_e32 v219, v177, v219
	v_cvt_pk_fp8_f32 v248, v0, v177
	v_add_f32_e32 v219, v179, v219
	v_add_f32_e32 v219, v254, v219
	v_cvt_pk_fp8_f32 v248, v179, v254 op_sel:[0,0,1]
	v_exp_f32_e32 v0, v94
	v_exp_f32_e32 v177, v95
	v_exp_f32_e32 v179, v96
	v_exp_f32_e32 v254, v97
	v_add_f32_e32 v219, v0, v219
	v_add_f32_e32 v219, v177, v219
	v_cvt_pk_fp8_f32 v249, v0, v177
	v_add_f32_e32 v219, v179, v219
	v_add_f32_e32 v219, v254, v219
	v_cvt_pk_fp8_f32 v249, v179, v254 op_sel:[0,0,1]
	ds_read_b128 v[90:93], v185 offset:59392
	ds_read_b128 v[94:97], v186 offset:59392
	s_waitcnt lgkmcnt(4)
	v_mfma_scale_f32_32x32x64_f8f6f4 v[114:129], v[82:89], v[138:145], v[114:129], v194, v193 op_sel_hi:[0,0,0]
	v_exp_f32_e32 v0, v66
	v_exp_f32_e32 v177, v67
	v_exp_f32_e32 v179, v68
	v_exp_f32_e32 v254, v69
	v_add_f32_e32 v219, v0, v219
	v_add_f32_e32 v219, v177, v219
	v_cvt_pk_fp8_f32 v250, v0, v177
	v_add_f32_e32 v219, v179, v219
	v_add_f32_e32 v219, v254, v219
	v_cvt_pk_fp8_f32 v250, v179, v254 op_sel:[0,0,1]
	s_waitcnt lgkmcnt(2)
	v_mfma_scale_f32_32x32x64_f8f6f4 v[98:113], v[222:229], v[138:145], v[98:113], v194, v193 op_sel_hi:[0,0,0]
	ds_read_b128 v[222:225], v185 offset:61440
	ds_read_b128 v[226:229], v186 offset:61440
	v_exp_f32_e32 v0, v70
	v_exp_f32_e32 v177, v71
	v_exp_f32_e32 v179, v72
	v_exp_f32_e32 v254, v73
	v_add_f32_e32 v219, v0, v219
	v_add_f32_e32 v219, v177, v219
	v_cvt_pk_fp8_f32 v251, v0, v177
	v_add_f32_e32 v219, v179, v219
	v_add_f32_e32 v219, v254, v219
	v_cvt_pk_fp8_f32 v251, v179, v254 op_sel:[0,0,1]
	v_exp_f32_e32 v0, v74
	v_exp_f32_e32 v177, v75
	v_exp_f32_e32 v179, v76
	v_exp_f32_e32 v254, v77
	v_add_f32_e32 v219, v0, v219
	v_add_f32_e32 v219, v177, v219
	v_cvt_pk_fp8_f32 v252, v0, v177
	v_add_f32_e32 v219, v179, v219
	v_add_f32_e32 v219, v254, v219
	v_cvt_pk_fp8_f32 v252, v179, v254 op_sel:[0,0,1]
	s_waitcnt lgkmcnt(2)
	v_mfma_scale_f32_32x32x64_f8f6f4 v[114:129], v[90:97], v[130:137], v[114:129], v194, v193 op_sel_hi:[0,0,0]
	v_exp_f32_e32 v0, v78
	v_exp_f32_e32 v177, v79
	v_exp_f32_e32 v179, v80
	v_exp_f32_e32 v254, v81
	v_add_f32_e32 v219, v0, v219
	v_add_f32_e32 v219, v177, v219
	v_cvt_pk_fp8_f32 v253, v0, v177
	v_add_f32_e32 v219, v179, v219
	v_add_f32_e32 v219, v254, v219
	v_cvt_pk_fp8_f32 v253, v179, v254 op_sel:[0,0,1]
	ds_read_b128 v[90:93], v185 offset:8192
	ds_read_b128 v[94:97], v186 offset:8192
	ds_read_b128 v[82:85], v185 offset:10240
	ds_read_b128 v[86:89], v186 offset:10240
	ds_read_b128 v[74:77], v185 offset:12288
	ds_read_b128 v[78:81], v186 offset:12288
	ds_read_b128 v[66:69], v185 offset:14336
	ds_read_b128 v[70:73], v186 offset:14336
	s_waitcnt lgkmcnt(8)
	v_mfma_scale_f32_32x32x64_f8f6f4 v[98:113], v[222:229], v[130:137], v[98:113], v194, v193 op_sel_hi:[0,0,0]
	v_mov_b32_e32 v0, v219
	s_nop 1
	v_permlane32_swap_b32_e32 v219, v0
	v_add_f32_e32 v219, v219, v0
	v_fma_f32 v209, v209, v218, v219
	v_max_f32_e32 v177, v114, v115
	v_max3_f32 v177, v177, v116, v117
	v_max3_f32 v177, v177, v118, v119
	v_max3_f32 v177, v177, v120, v121
	v_max3_f32 v177, v177, v122, v123
	v_max3_f32 v177, v177, v124, v125
	v_max3_f32 v177, v177, v126, v127
	v_max3_f32 v177, v177, v128, v129
	s_waitcnt lgkmcnt(6)
	v_mfma_scale_f32_32x32x64_f8f6f4 v[50:65], v[246:253], v[90:97], v[50:65], v194, v194 op_sel_hi:[0,0,0]
	s_waitcnt lgkmcnt(4)
	v_mfma_scale_f32_32x32x64_f8f6f4 v[34:49], v[246:253], v[82:89], v[34:49], v194, v194 op_sel_hi:[0,0,0]
	s_waitcnt vmcnt(0)
	ds_write_b128 v210, v[158:161]
	ds_write_b128 v211, v[162:165] offset:16384
	ds_write_b128 v212, v[154:157] offset:32768
	s_waitcnt lgkmcnt(5)
	v_mfma_scale_f32_32x32x64_f8f6f4 v[18:33], v[246:253], v[74:81], v[18:33], v194, v194 op_sel_hi:[0,0,0]
	s_waitcnt lgkmcnt(3)
	v_mfma_scale_f32_32x32x64_f8f6f4 v[2:17], v[246:253], v[66:73], v[2:17], v194, v194 op_sel_hi:[0,0,0]
	s_waitcnt lgkmcnt(0)
	s_barrier
	v_max_f32_e32 v0, v98, v99
	v_max3_f32 v0, v0, v100, v101
	v_max3_f32 v0, v0, v102, v103
	v_max3_f32 v0, v0, v104, v105
	v_max3_f32 v0, v0, v106, v107
	v_max3_f32 v0, v0, v108, v109
	v_max3_f32 v0, v0, v110, v111
	v_max3_f32 v0, v0, v112, v113
	v_max_f32_e32 v177, v177, v0
	v_mov_b32_e32 v0, v177
	v_mov_b32_e32 v221, 1.0
	s_nop 0
	v_permlane32_swap_b32_e32 v177, v0
	v_max_f32_e32 v177, v177, v0
	v_cmp_ge_f32_e32 vcc, s90, v177
	s_cmp_eq_u64 vcc, exec
	s_cbranch_scc0 .Lmla_h4_newmax
; __device__ __forceinline__ void finishSM9(f32x16& p0, f32x16& p1, float alpha, float& l_reg, v8i32& p8) {
; #pragma unroll
;   for (int r = 0; r < 16; ++r) { p0[r] = __builtin_amdgcn_exp2f(p0[r]); p1[r] = __builtin_amdgcn_exp2f(p1[r]); }
;   float ps = 0;
; #pragma unroll
;   for (int r = 0; r < 16; ++r) ps += p0[r];
; #pragma unroll
;   for (int r = 0; r < 16; ++r) ps += p1[r];
;   { auto rr = __builtin_amdgcn_permlane32_swap(__float_as_uint(ps), __float_as_uint(ps), false, false);
;     ps = __uint_as_float(rr[0]) + __uint_as_float(rr[1]); }
;   l_reg = l_reg * alpha + ps;
; #pragma unroll
;   for (int g = 0; g < 4; ++g) {
;     int w = __builtin_amdgcn_cvt_pk_fp8_f32(p0[4 * g], p0[4 * g + 1], 0, false); p8[g] = __builtin_amdgcn_cvt_pk_fp8_f32(p0[4 * g + 2], p0[4 * g + 3], w, true);
;     int u = __builtin_amdgcn_cvt_pk_fp8_f32(p1[4 * g], p1[4 * g + 1], 0, false); p8[4 + g] = __builtin_amdgcn_cvt_pk_fp8_f32(p1[4 * g + 2], p1[4 * g + 3], u, true); }
; }
; __device__ __forceinline__ void pv8(f32x16* o, const char* Vt, const v8i32 p8, int r32, int hi) {
;   const int sw = (r32 >> 2) & 3, a0 = r32 * 64 + (((hi * 2) ^ sw) << 4), a1 = r32 * 64 + (((hi * 2 + 1) ^ sw) << 4);
; #pragma unroll
;   for (int d0 = 0; d0 < 4; ++d0) {
;     const v8i32 vf = cat8(*reinterpret_cast<const v4i32*>(Vt + d0 * 2048 + a0), *reinterpret_cast<const v4i32*>(Vt + d0 * 2048 + a1));
;     o[d0] = __builtin_amdgcn_mfma_scale_f32_32x32x64_f8f6f4(p8, vf, o[d0], 0, 0, 0, 127, 0, 127); }
; }
; __device__ __forceinline__ void qkt9(f32x16& p0, f32x16& p1, const char* Kn, const char* Kr, const v8i32* qf, const float init, int r32, int hi) {
; #pragma unroll
;   for (int r = 0; r < 16; ++r) { p0[r] = init; p1[r] = init; }
; #pragma unroll
;   for (int s = 0; s < 2; ++s) { const int c0 = s * 4 + hi * 2;
;     const v8i32 a0 = cat8(*reinterpret_cast<const v4i32*>(Kn + KN8SW(r32, c0)), *reinterpret_cast<const v4i32*>(Kn + KN8SW(r32, c0 + 1)));
;     const v8i32 a1 = cat8(*reinterpret_cast<const v4i32*>(Kn + 4096 + KN8SW(r32, c0)), *reinterpret_cast<const v4i32*>(Kn + 4096 + KN8SW(r32, c0 + 1)));
;     p0 = __builtin_amdgcn_mfma_scale_f32_32x32x64_f8f6f4(a0, qf[s], p0, 0, 0, 0, 127, 0, 124);
;     p1 = __builtin_amdgcn_mfma_scale_f32_32x32x64_f8f6f4(a1, qf[s], p1, 0, 0, 0, 127, 0, 124); }
;   { const int c0 = hi * 2;
.Lmla_h4_cont:
	global_load_dwordx4 v[158:161], v176, s[18:19]
	global_load_dwordx4 v[162:165], v178, s[16:17]
	global_load_dwordx4 v[154:157], v[180:181], off
	ds_read_b128 v[82:85], v215 offset:16384
	ds_read_b128 v[86:89], v216 offset:16384
	ds_read_b128 v[222:225], v215 offset:20480
	ds_read_b128 v[226:229], v216 offset:20480
	v_add_u32_e32 v176, 0x2000, v176
	v_add_u32_e32 v178, 0x20000, v178
	s_mov_b64 s[20:21], 0x1000
	v_lshl_add_u64 v[180:181], v[180:181], 0, s[20:21]
	v_exp_f32_e32 v0, v114
	v_exp_f32_e32 v177, v115
	v_exp_f32_e32 v179, v116
	v_exp_f32_e32 v254, v117
	v_add_f32_e32 v219, v0, v177
	v_cvt_pk_fp8_f32 v246, v0, v177
	v_add_f32_e32 v219, v179, v219
	v_add_f32_e32 v219, v254, v219
	v_cvt_pk_fp8_f32 v246, v179, v254 op_sel:[0,0,1]
	s_waitcnt lgkmcnt(2)
	v_mfma_scale_f32_32x32x64_f8f6f4 v[82:97], v[82:89], v[146:153], v[230:245], v194, v193 op_sel_hi:[0,0,0]
	v_exp_f32_e32 v0, v118
	v_exp_f32_e32 v177, v119
	v_exp_f32_e32 v179, v120
	v_exp_f32_e32 v254, v121
	v_add_f32_e32 v219, v0, v219
	v_add_f32_e32 v219, v177, v219
	v_cvt_pk_fp8_f32 v247, v0, v177
	v_add_f32_e32 v219, v179, v219
	v_add_f32_e32 v219, v254, v219
	v_cvt_pk_fp8_f32 v247, v179, v254 op_sel:[0,0,1]
	ds_read_b128 v[114:117], v213 offset:16384
	ds_read_b128 v[118:121], v214 offset:16384
	s_waitcnt lgkmcnt(2)
	v_mfma_scale_f32_32x32x64_f8f6f4 v[66:81], v[222:229], v[146:153], v[230:245], v194, v193 op_sel_hi:[0,0,0]
	ds_read_b128 v[222:225], v213 offset:20480
	ds_read_b128 v[226:229], v214 offset:20480
	v_exp_f32_e32 v0, v122
	v_exp_f32_e32 v177, v123
	v_exp_f32_e32 v179, v124
	v_exp_f32_e32 v254, v125
	v_add_f32_e32 v219, v0, v219
	v_add_f32_e32 v219, v177, v219
	v_cvt_pk_fp8_f32 v248, v0, v177
	v_add_f32_e32 v219, v179, v219
	v_add_f32_e32 v219, v254, v219
	v_cvt_pk_fp8_f32 v248, v179, v254 op_sel:[0,0,1]
	v_exp_f32_e32 v0, v126
	v_exp_f32_e32 v177, v127
	v_exp_f32_e32 v179, v128
	v_exp_f32_e32 v254, v129
	v_add_f32_e32 v219, v0, v219
	v_add_f32_e32 v219, v177, v219
	v_cvt_pk_fp8_f32 v249, v0, v177
	v_add_f32_e32 v219, v179, v219
	v_add_f32_e32 v219, v254, v219
	v_cvt_pk_fp8_f32 v249, v179, v254 op_sel:[0,0,1]
	ds_read_b128 v[122:125], v185 offset:32768
	ds_read_b128 v[126:129], v186 offset:32768
	s_waitcnt lgkmcnt(4)
	v_mfma_scale_f32_32x32x64_f8f6f4 v[82:97], v[114:121], v[138:145], v[82:97], v194, v193 op_sel_hi:[0,0,0]
	v_exp_f32_e32 v0, v98
	v_exp_f32_e32 v177, v99
	v_exp_f32_e32 v179, v100
	v_exp_f32_e32 v254, v101
	v_add_f32_e32 v219, v0, v219
	v_add_f32_e32 v219, v177, v219
	v_cvt_pk_fp8_f32 v250, v0, v177
	v_add_f32_e32 v219, v179, v219
	v_add_f32_e32 v219, v254, v219
	v_cvt_pk_fp8_f32 v250, v179, v254 op_sel:[0,0,1]
	s_waitcnt lgkmcnt(2)
	v_mfma_scale_f32_32x32x64_f8f6f4 v[66:81], v[222:229], v[138:145], v[66:81], v194, v193 op_sel_hi:[0,0,0]
	ds_read_b128 v[222:225], v185 offset:34816
	ds_read_b128 v[226:229], v186 offset:34816
	v_exp_f32_e32 v0, v102
	v_exp_f32_e32 v177, v103
	v_exp_f32_e32 v179, v104
	v_exp_f32_e32 v254, v105
	v_add_f32_e32 v219, v0, v219
	v_add_f32_e32 v219, v177, v219
	v_cvt_pk_fp8_f32 v251, v0, v177
	v_add_f32_e32 v219, v179, v219
	v_add_f32_e32 v219, v254, v219
	v_cvt_pk_fp8_f32 v251, v179, v254 op_sel:[0,0,1]
	v_exp_f32_e32 v0, v106
	v_exp_f32_e32 v177, v107
	v_exp_f32_e32 v179, v108
	v_exp_f32_e32 v254, v109
	v_add_f32_e32 v219, v0, v219
	v_add_f32_e32 v219, v177, v219
	v_cvt_pk_fp8_f32 v252, v0, v177
	v_add_f32_e32 v219, v179, v219
	v_add_f32_e32 v219, v254, v219
	v_cvt_pk_fp8_f32 v252, v179, v254 op_sel:[0,0,1]
	s_waitcnt lgkmcnt(2)
	v_mfma_scale_f32_32x32x64_f8f6f4 v[82:97], v[122:129], v[130:137], v[82:97], v194, v193 op_sel_hi:[0,0,0]
	v_exp_f32_e32 v0, v110
	v_exp_f32_e32 v177, v111
	v_exp_f32_e32 v179, v112
	v_exp_f32_e32 v254, v113
	v_add_f32_e32 v219, v0, v219
	v_add_f32_e32 v219, v177, v219
	v_cvt_pk_fp8_f32 v253, v0, v177
	v_add_f32_e32 v219, v179, v219
	v_add_f32_e32 v219, v254, v219
	v_cvt_pk_fp8_f32 v253, v179, v254 op_sel:[0,0,1]
	ds_read_b128 v[122:125], v185 offset:43008
	ds_read_b128 v[126:129], v186 offset:43008
	ds_read_b128 v[114:117], v185 offset:45056
	ds_read_b128 v[118:121], v186 offset:45056
	ds_read_b128 v[106:109], v185 offset:47104
	ds_read_b128 v[110:113], v186 offset:47104
	ds_read_b128 v[98:101], v185 offset:49152
	ds_read_b128 v[102:105], v186 offset:49152
	s_waitcnt lgkmcnt(8)
	v_mfma_scale_f32_32x32x64_f8f6f4 v[66:81], v[222:229], v[130:137], v[66:81], v194, v193 op_sel_hi:[0,0,0]
	v_mov_b32_e32 v0, v219
	s_nop 1
	v_permlane32_swap_b32_e32 v219, v0
	v_add_f32_e32 v219, v219, v0
	v_fma_f32 v209, v209, v221, v219
	v_max_f32_e32 v177, v82, v83
	v_max3_f32 v177, v177, v84, v85
	v_max3_f32 v177, v177, v86, v87
	v_max3_f32 v177, v177, v88, v89
	v_max3_f32 v177, v177, v90, v91
	v_max3_f32 v177, v177, v92, v93
	v_max3_f32 v177, v177, v94, v95
	v_max3_f32 v177, v177, v96, v97
	s_waitcnt lgkmcnt(6)
	v_mfma_scale_f32_32x32x64_f8f6f4 v[50:65], v[246:253], v[122:129], v[50:65], v194, v194 op_sel_hi:[0,0,0]
	s_waitcnt lgkmcnt(4)
	v_mfma_scale_f32_32x32x64_f8f6f4 v[34:49], v[246:253], v[114:121], v[34:49], v194, v194 op_sel_hi:[0,0,0]
	s_waitcnt vmcnt(0)
	ds_write_b128 v210, v[158:161] offset:8192
	ds_write_b128 v211, v[162:165] offset:24576
	ds_write_b128 v212, v[154:157] offset:36864
	s_waitcnt lgkmcnt(5)
	v_mfma_scale_f32_32x32x64_f8f6f4 v[18:33], v[246:253], v[106:113], v[18:33], v194, v194 op_sel_hi:[0,0,0]
	s_waitcnt lgkmcnt(3)
	v_mfma_scale_f32_32x32x64_f8f6f4 v[2:17], v[246:253], v[98:105], v[2:17], v194, v194 op_sel_hi:[0,0,0]
	s_waitcnt lgkmcnt(0)
	s_barrier
	v_max_f32_e32 v0, v66, v67
	v_max3_f32 v0, v0, v68, v69
	v_max3_f32 v0, v0, v70, v71
	v_max3_f32 v0, v0, v72, v73
	v_max3_f32 v0, v0, v74, v75
	v_max3_f32 v0, v0, v76, v77
	v_max3_f32 v0, v0, v78, v79
	v_max3_f32 v0, v0, v80, v81
	v_max_f32_e32 v177, v177, v0
	v_mov_b32_e32 v0, v177
	v_mov_b32_e32 v218, 1.0
	s_nop 0
	v_permlane32_swap_b32_e32 v177, v0
	v_max_f32_e32 v177, v177, v0
	v_cmp_ge_f32_e32 vcc, s90, v177
	s_cmp_eq_u64 vcc, exec
	s_cbranch_scc0 .Lmla_h5_newmax
; __device__ __forceinline__ void finishSM9(f32x16& p0, f32x16& p1, float alpha, float& l_reg, v8i32& p8) {
; #pragma unroll
;   for (int r = 0; r < 16; ++r) { p0[r] = __builtin_amdgcn_exp2f(p0[r]); p1[r] = __builtin_amdgcn_exp2f(p1[r]); }
;   float ps = 0;
; #pragma unroll
;   for (int r = 0; r < 16; ++r) ps += p0[r];
; #pragma unroll
;   for (int r = 0; r < 16; ++r) ps += p1[r];
;   { auto rr = __builtin_amdgcn_permlane32_swap(__float_as_uint(ps), __float_as_uint(ps), false, false);
;     ps = __uint_as_float(rr[0]) + __uint_as_float(rr[1]); }
;   l_reg = l_reg * alpha + ps;
; #pragma unroll
;   for (int g = 0; g < 4; ++g) {
;     int w = __builtin_amdgcn_cvt_pk_fp8_f32(p0[4 * g], p0[4 * g + 1], 0, false); p8[g] = __builtin_amdgcn_cvt_pk_fp8_f32(p0[4 * g + 2], p0[4 * g + 3], w, true);
;     int u = __builtin_amdgcn_cvt_pk_fp8_f32(p1[4 * g], p1[4 * g + 1], 0, false); p8[4 + g] = __builtin_amdgcn_cvt_pk_fp8_f32(p1[4 * g + 2], p1[4 * g + 3], u, true); }
; }
; __device__ __forceinline__ void pv8(f32x16* o, const char* Vt, const v8i32 p8, int r32, int hi) {
;   const int sw = (r32 >> 2) & 3, a0 = r32 * 64 + (((hi * 2) ^ sw) << 4), a1 = r32 * 64 + (((hi * 2 + 1) ^ sw) << 4);
; #pragma unroll
;   for (int d0 = 0; d0 < 4; ++d0) {
;     const v8i32 vf = cat8(*reinterpret_cast<const v4i32*>(Vt + d0 * 2048 + a0), *reinterpret_cast<const v4i32*>(Vt + d0 * 2048 + a1));
;     o[d0] = __builtin_amdgcn_mfma_scale_f32_32x32x64_f8f6f4(p8, vf, o[d0], 0, 0, 0, 127, 0, 127); }
; }
; __device__ __forceinline__ void qkt9(f32x16& p0, f32x16& p1, const char* Kn, const char* Kr, const v8i32* qf, const float init, int r32, int hi) {
; #pragma unroll
;   for (int r = 0; r < 16; ++r) { p0[r] = init; p1[r] = init; }
; #pragma unroll
;   for (int s = 0; s < 2; ++s) { const int c0 = s * 4 + hi * 2;
;     const v8i32 a0 = cat8(*reinterpret_cast<const v4i32*>(Kn + KN8SW(r32, c0)), *reinterpret_cast<const v4i32*>(Kn + KN8SW(r32, c0 + 1)));
;     const v8i32 a1 = cat8(*reinterpret_cast<const v4i32*>(Kn + 4096 + KN8SW(r32, c0)), *reinterpret_cast<const v4i32*>(Kn + 4096 + KN8SW(r32, c0 + 1)));
;     p0 = __builtin_amdgcn_mfma_scale_f32_32x32x64_f8f6f4(a0, qf[s], p0, 0, 0, 0, 127, 0, 124);
;     p1 = __builtin_amdgcn_mfma_scale_f32_32x32x64_f8f6f4(a1, qf[s], p1, 0, 0, 0, 127, 0, 124); }
;   { const int c0 = hi * 2;
.Lmla_h5_cont:
	s_add_i32 s30, s30, 1
	s_cmpk_lt_u32 s30, 42
	s_cbranch_scc1 .LBB0_1321
	global_load_dwordx4 v[158:161], v176, s[18:19]
	global_load_dwordx4 v[162:165], v178, s[16:17]
	global_load_dwordx4 v[154:157], v[180:181], off
	ds_read_b128 v[114:117], v215 offset:24576
	ds_read_b128 v[118:121], v216 offset:24576
	ds_read_b128 v[222:225], v215 offset:28672
	ds_read_b128 v[226:229], v216 offset:28672
	v_add_u32_e32 v176, 0x2000, v176
	v_add_u32_e32 v178, 0x20000, v178
	s_mov_b64 s[20:21], 0x1000
	v_lshl_add_u64 v[180:181], v[180:181], 0, s[20:21]
	v_exp_f32_e32 v0, v82
	v_exp_f32_e32 v177, v83
	v_exp_f32_e32 v179, v84
	v_exp_f32_e32 v254, v85
	v_add_f32_e32 v219, v0, v177
	v_cvt_pk_fp8_f32 v246, v0, v177
	v_add_f32_e32 v219, v179, v219
	v_add_f32_e32 v219, v254, v219
	v_cvt_pk_fp8_f32 v246, v179, v254 op_sel:[0,0,1]
	s_waitcnt lgkmcnt(2)
	v_mfma_scale_f32_32x32x64_f8f6f4 v[114:129], v[114:121], v[146:153], v[230:245], v194, v193 op_sel_hi:[0,0,0]
	v_exp_f32_e32 v0, v86
	v_exp_f32_e32 v177, v87
	v_exp_f32_e32 v179, v88
	v_exp_f32_e32 v254, v89
	v_add_f32_e32 v219, v0, v219
	v_add_f32_e32 v219, v177, v219
	v_cvt_pk_fp8_f32 v247, v0, v177
	v_add_f32_e32 v219, v179, v219
	v_add_f32_e32 v219, v254, v219
	v_cvt_pk_fp8_f32 v247, v179, v254 op_sel:[0,0,1]
	ds_read_b128 v[82:85], v213 offset:24576
	ds_read_b128 v[86:89], v214 offset:24576
	s_waitcnt lgkmcnt(2)
	v_mfma_scale_f32_32x32x64_f8f6f4 v[98:113], v[222:229], v[146:153], v[230:245], v194, v193 op_sel_hi:[0,0,0]
	ds_read_b128 v[222:225], v213 offset:28672
	ds_read_b128 v[226:229], v214 offset:28672
	v_exp_f32_e32 v0, v90
	v_exp_f32_e32 v177, v91
	v_exp_f32_e32 v179, v92
	v_exp_f32_e32 v254, v93
	v_add_f32_e32 v219, v0, v219
	v_add_f32_e32 v219, v177, v219
	v_cvt_pk_fp8_f32 v248, v0, v177
	v_add_f32_e32 v219, v179, v219
	v_add_f32_e32 v219, v254, v219
	v_cvt_pk_fp8_f32 v248, v179, v254 op_sel:[0,0,1]
	v_exp_f32_e32 v0, v94
	v_exp_f32_e32 v177, v95
	v_exp_f32_e32 v179, v96
	v_exp_f32_e32 v254, v97
	v_add_f32_e32 v219, v0, v219
	v_add_f32_e32 v219, v177, v219
	v_cvt_pk_fp8_f32 v249, v0, v177
	v_add_f32_e32 v219, v179, v219
	v_add_f32_e32 v219, v254, v219
	v_cvt_pk_fp8_f32 v249, v179, v254 op_sel:[0,0,1]
	ds_read_b128 v[90:93], v185 offset:36864
	ds_read_b128 v[94:97], v186 offset:36864
	s_waitcnt lgkmcnt(4)
	v_mfma_scale_f32_32x32x64_f8f6f4 v[114:129], v[82:89], v[138:145], v[114:129], v194, v193 op_sel_hi:[0,0,0]
	v_exp_f32_e32 v0, v66
	v_exp_f32_e32 v177, v67
	v_exp_f32_e32 v179, v68
	v_exp_f32_e32 v254, v69
	v_add_f32_e32 v219, v0, v219
	v_add_f32_e32 v219, v177, v219
	v_cvt_pk_fp8_f32 v250, v0, v177
	v_add_f32_e32 v219, v179, v219
	v_add_f32_e32 v219, v254, v219
	v_cvt_pk_fp8_f32 v250, v179, v254 op_sel:[0,0,1]
	s_waitcnt lgkmcnt(2)
	v_mfma_scale_f32_32x32x64_f8f6f4 v[98:113], v[222:229], v[138:145], v[98:113], v194, v193 op_sel_hi:[0,0,0]
	ds_read_b128 v[222:225], v185 offset:38912
	ds_read_b128 v[226:229], v186 offset:38912
	v_exp_f32_e32 v0, v70
	v_exp_f32_e32 v177, v71
	v_exp_f32_e32 v179, v72
	v_exp_f32_e32 v254, v73
	v_add_f32_e32 v219, v0, v219
	v_add_f32_e32 v219, v177, v219
	v_cvt_pk_fp8_f32 v251, v0, v177
	v_add_f32_e32 v219, v179, v219
	v_add_f32_e32 v219, v254, v219
	v_cvt_pk_fp8_f32 v251, v179, v254 op_sel:[0,0,1]
	v_exp_f32_e32 v0, v74
	v_exp_f32_e32 v177, v75
	v_exp_f32_e32 v179, v76
	v_exp_f32_e32 v254, v77
	v_add_f32_e32 v219, v0, v219
	v_add_f32_e32 v219, v177, v219
	v_cvt_pk_fp8_f32 v252, v0, v177
	v_add_f32_e32 v219, v179, v219
	v_add_f32_e32 v219, v254, v219
	v_cvt_pk_fp8_f32 v252, v179, v254 op_sel:[0,0,1]
	s_waitcnt lgkmcnt(2)
	v_mfma_scale_f32_32x32x64_f8f6f4 v[114:129], v[90:97], v[130:137], v[114:129], v194, v193 op_sel_hi:[0,0,0]
	v_exp_f32_e32 v0, v78
	v_exp_f32_e32 v177, v79
	v_exp_f32_e32 v179, v80
	v_exp_f32_e32 v254, v81
	v_add_f32_e32 v219, v0, v219
	v_add_f32_e32 v219, v177, v219
	v_cvt_pk_fp8_f32 v253, v0, v177
	v_add_f32_e32 v219, v179, v219
	v_add_f32_e32 v219, v254, v219
	v_cvt_pk_fp8_f32 v253, v179, v254 op_sel:[0,0,1]
	ds_read_b128 v[90:93], v185 offset:0
	ds_read_b128 v[94:97], v186 offset:0
	ds_read_b128 v[82:85], v185 offset:2048
	ds_read_b128 v[86:89], v186 offset:2048
	ds_read_b128 v[74:77], v185 offset:4096
	ds_read_b128 v[78:81], v186 offset:4096
	ds_read_b128 v[66:69], v185 offset:6144
	ds_read_b128 v[70:73], v186 offset:6144
	s_waitcnt lgkmcnt(8)
	v_mfma_scale_f32_32x32x64_f8f6f4 v[98:113], v[222:229], v[130:137], v[98:113], v194, v193 op_sel_hi:[0,0,0]
	v_mov_b32_e32 v0, v219
	s_nop 1
	v_permlane32_swap_b32_e32 v219, v0
	v_add_f32_e32 v219, v219, v0
	v_fma_f32 v209, v209, v218, v219
	v_max_f32_e32 v177, v114, v115
	v_max3_f32 v177, v177, v116, v117
	v_max3_f32 v177, v177, v118, v119
	v_max3_f32 v177, v177, v120, v121
	v_max3_f32 v177, v177, v122, v123
	v_max3_f32 v177, v177, v124, v125
	v_max3_f32 v177, v177, v126, v127
	v_max3_f32 v177, v177, v128, v129
	s_waitcnt lgkmcnt(6)
	v_mfma_scale_f32_32x32x64_f8f6f4 v[50:65], v[246:253], v[90:97], v[50:65], v194, v194 op_sel_hi:[0,0,0]
	s_waitcnt lgkmcnt(4)
	v_mfma_scale_f32_32x32x64_f8f6f4 v[34:49], v[246:253], v[82:89], v[34:49], v194, v194 op_sel_hi:[0,0,0]
	s_waitcnt vmcnt(0)
	ds_write_b128 v210, v[158:161] offset:43008
	ds_write_b128 v211, v[162:165] offset:51200
	ds_write_b128 v212, v[154:157] offset:59392
	s_waitcnt lgkmcnt(5)
	v_mfma_scale_f32_32x32x64_f8f6f4 v[18:33], v[246:253], v[74:81], v[18:33], v194, v194 op_sel_hi:[0,0,0]
	s_waitcnt lgkmcnt(3)
	v_mfma_scale_f32_32x32x64_f8f6f4 v[2:17], v[246:253], v[66:73], v[2:17], v194, v194 op_sel_hi:[0,0,0]
	s_waitcnt lgkmcnt(0)
	s_barrier
	v_max_f32_e32 v0, v98, v99
	v_max3_f32 v0, v0, v100, v101
	v_max3_f32 v0, v0, v102, v103
	v_max3_f32 v0, v0, v104, v105
	v_max3_f32 v0, v0, v106, v107
	v_max3_f32 v0, v0, v108, v109
	v_max3_f32 v0, v0, v110, v111
	v_max3_f32 v0, v0, v112, v113
	v_max_f32_e32 v177, v177, v0
	v_mov_b32_e32 v0, v177
	v_mov_b32_e32 v221, 1.0
	s_nop 0
	v_permlane32_swap_b32_e32 v177, v0
	v_max_f32_e32 v177, v177, v0
	v_cmp_ge_f32_e32 vcc, s90, v177
	s_cmp_eq_u64 vcc, exec
	s_cbranch_scc0 .Lmla_p0_newmax

; __device__ __forceinline__ void finishSM9(f32x16& p0, f32x16& p1, float alpha, float& l_reg, v8i32& p8) {
; #pragma unroll
;   for (int r = 0; r < 16; ++r) { p0[r] = __builtin_amdgcn_exp2f(p0[r]); p1[r] = __builtin_amdgcn_exp2f(p1[r]); }
;   float ps = 0;
; #pragma unroll
;   for (int r = 0; r < 16; ++r) ps += p0[r];
; #pragma unroll
;   for (int r = 0; r < 16; ++r) ps += p1[r];
;   { auto rr = __builtin_amdgcn_permlane32_swap(__float_as_uint(ps), __float_as_uint(ps), false, false);
;     ps = __uint_as_float(rr[0]) + __uint_as_float(rr[1]); }
;   l_reg = l_reg * alpha + ps;
; #pragma unroll
;   for (int g = 0; g < 4; ++g) {
;     int w = __builtin_amdgcn_cvt_pk_fp8_f32(p0[4 * g], p0[4 * g + 1], 0, false); p8[g] = __builtin_amdgcn_cvt_pk_fp8_f32(p0[4 * g + 2], p0[4 * g + 3], w, true);
;     int u = __builtin_amdgcn_cvt_pk_fp8_f32(p1[4 * g], p1[4 * g + 1], 0, false); p8[4 + g] = __builtin_amdgcn_cvt_pk_fp8_f32(p1[4 * g + 2], p1[4 * g + 3], u, true); }
; }
; __device__ __forceinline__ void pv8(f32x16* o, const char* Vt, const v8i32 p8, int r32, int hi) {
;   const int sw = (r32 >> 2) & 3, a0 = r32 * 64 + (((hi * 2) ^ sw) << 4), a1 = r32 * 64 + (((hi * 2 + 1) ^ sw) << 4);
; #pragma unroll
;   for (int d0 = 0; d0 < 4; ++d0) {
;     const v8i32 vf = cat8(*reinterpret_cast<const v4i32*>(Vt + d0 * 2048 + a0), *reinterpret_cast<const v4i32*>(Vt + d0 * 2048 + a1));
;     o[d0] = __builtin_amdgcn_mfma_scale_f32_32x32x64_f8f6f4(p8, vf, o[d0], 0, 0, 0, 127, 0, 127); }
; }
; __device__ __forceinline__ void qkt9(f32x16& p0, f32x16& p1, const char* Kn, const char* Kr, const v8i32* qf, const float init, int r32, int hi) {
; #pragma unroll
;   for (int r = 0; r < 16; ++r) { p0[r] = init; p1[r] = init; }
; #pragma unroll
;   for (int s = 0; s < 2; ++s) { const int c0 = s * 4 + hi * 2;
;     const v8i32 a0 = cat8(*reinterpret_cast<const v4i32*>(Kn + KN8SW(r32, c0)), *reinterpret_cast<const v4i32*>(Kn + KN8SW(r32, c0 + 1)));
;     const v8i32 a1 = cat8(*reinterpret_cast<const v4i32*>(Kn + 4096 + KN8SW(r32, c0)), *reinterpret_cast<const v4i32*>(Kn + 4096 + KN8SW(r32, c0 + 1)));
;     p0 = __builtin_amdgcn_mfma_scale_f32_32x32x64_f8f6f4(a0, qf[s], p0, 0, 0, 0, 127, 0, 124);
;     p1 = __builtin_amdgcn_mfma_scale_f32_32x32x64_f8f6f4(a1, qf[s], p1, 0, 0, 0, 127, 0, 124); }
;   { const int c0 = hi * 2;
.Lmla_stag_loop:
	ds_read_b128 v[114:117], v215 offset:24576
	ds_read_b128 v[118:121], v216 offset:24576
	ds_read_b128 v[222:225], v215 offset:28672
	ds_read_b128 v[226:229], v216 offset:28672
	v_exp_f32_e32 v0, v82
	v_exp_f32_e32 v177, v83
	v_exp_f32_e32 v179, v84
	v_exp_f32_e32 v254, v85
	v_add_f32_e32 v219, v0, v177
	v_cvt_pk_fp8_f32 v246, v0, v177
	v_add_f32_e32 v219, v179, v219
	v_add_f32_e32 v219, v254, v219
	v_cvt_pk_fp8_f32 v246, v179, v254 op_sel:[0,0,1]
	s_waitcnt lgkmcnt(2)
	v_mfma_scale_f32_32x32x64_f8f6f4 v[114:129], v[114:121], v[146:153], v[230:245], v194, v193 op_sel_hi:[0,0,0]
	v_exp_f32_e32 v0, v86
	v_exp_f32_e32 v177, v87
	v_exp_f32_e32 v179, v88
	v_exp_f32_e32 v254, v89
	v_add_f32_e32 v219, v0, v219
	v_add_f32_e32 v219, v177, v219
	v_cvt_pk_fp8_f32 v247, v0, v177
	v_add_f32_e32 v219, v179, v219
	v_add_f32_e32 v219, v254, v219
	v_cvt_pk_fp8_f32 v247, v179, v254 op_sel:[0,0,1]
	ds_read_b128 v[82:85], v213 offset:24576
	ds_read_b128 v[86:89], v214 offset:24576
	s_waitcnt lgkmcnt(2)
	v_mfma_scale_f32_32x32x64_f8f6f4 v[98:113], v[222:229], v[146:153], v[230:245], v194, v193 op_sel_hi:[0,0,0]
	ds_read_b128 v[222:225], v213 offset:28672
	ds_read_b128 v[226:229], v214 offset:28672
	v_exp_f32_e32 v0, v90
	v_exp_f32_e32 v177, v91
	v_exp_f32_e32 v179, v92
	v_exp_f32_e32 v254, v93
	v_add_f32_e32 v219, v0, v219
	v_add_f32_e32 v219, v177, v219
	v_cvt_pk_fp8_f32 v248, v0, v177
	v_add_f32_e32 v219, v179, v219
	v_add_f32_e32 v219, v254, v219
	v_cvt_pk_fp8_f32 v248, v179, v254 op_sel:[0,0,1]
	v_exp_f32_e32 v0, v94
	v_exp_f32_e32 v177, v95
	v_exp_f32_e32 v179, v96
	v_exp_f32_e32 v254, v97
	v_add_f32_e32 v219, v0, v219
	v_add_f32_e32 v219, v177, v219
	v_cvt_pk_fp8_f32 v249, v0, v177
	v_add_f32_e32 v219, v179, v219
	v_add_f32_e32 v219, v254, v219
	v_cvt_pk_fp8_f32 v249, v179, v254 op_sel:[0,0,1]
	ds_read_b128 v[90:93], v185 offset:36864
	ds_read_b128 v[94:97], v186 offset:36864
	s_waitcnt lgkmcnt(4)
	v_mfma_scale_f32_32x32x64_f8f6f4 v[114:129], v[82:89], v[138:145], v[114:129], v194, v193 op_sel_hi:[0,0,0]
	v_exp_f32_e32 v0, v66
	v_exp_f32_e32 v177, v67
	v_exp_f32_e32 v179, v68
	v_exp_f32_e32 v254, v69
	v_add_f32_e32 v219, v0, v219
	v_add_f32_e32 v219, v177, v219
	v_cvt_pk_fp8_f32 v250, v0, v177
	v_add_f32_e32 v219, v179, v219
	v_add_f32_e32 v219, v254, v219
	v_cvt_pk_fp8_f32 v250, v179, v254 op_sel:[0,0,1]
	s_waitcnt lgkmcnt(2)
	v_mfma_scale_f32_32x32x64_f8f6f4 v[98:113], v[222:229], v[138:145], v[98:113], v194, v193 op_sel_hi:[0,0,0]
	ds_read_b128 v[222:225], v185 offset:38912
	ds_read_b128 v[226:229], v186 offset:38912
	v_exp_f32_e32 v0, v70
	v_exp_f32_e32 v177, v71
	v_exp_f32_e32 v179, v72
	v_exp_f32_e32 v254, v73
	v_add_f32_e32 v219, v0, v219
	v_add_f32_e32 v219, v177, v219
	v_cvt_pk_fp8_f32 v251, v0, v177
	v_add_f32_e32 v219, v179, v219
	v_add_f32_e32 v219, v254, v219
	v_cvt_pk_fp8_f32 v251, v179, v254 op_sel:[0,0,1]
	v_exp_f32_e32 v0, v74
	v_exp_f32_e32 v177, v75
	v_exp_f32_e32 v179, v76
	v_exp_f32_e32 v254, v77
	v_add_f32_e32 v219, v0, v219
	v_add_f32_e32 v219, v177, v219
	v_cvt_pk_fp8_f32 v252, v0, v177
	v_add_f32_e32 v219, v179, v219
	v_add_f32_e32 v219, v254, v219
	v_cvt_pk_fp8_f32 v252, v179, v254 op_sel:[0,0,1]
	s_waitcnt lgkmcnt(2)
	v_mfma_scale_f32_32x32x64_f8f6f4 v[114:129], v[90:97], v[130:137], v[114:129], v194, v193 op_sel_hi:[0,0,0]
	v_exp_f32_e32 v0, v78
	v_exp_f32_e32 v177, v79
	v_exp_f32_e32 v179, v80
	v_exp_f32_e32 v254, v81
	v_add_f32_e32 v219, v0, v219
	v_add_f32_e32 v219, v177, v219
	v_cvt_pk_fp8_f32 v253, v0, v177
	v_add_f32_e32 v219, v179, v219
	v_add_f32_e32 v219, v254, v219
	v_cvt_pk_fp8_f32 v253, v179, v254 op_sel:[0,0,1]
	ds_read_b128 v[90:93], v185 offset:0
	ds_read_b128 v[94:97], v186 offset:0
	ds_read_b128 v[82:85], v185 offset:2048
	ds_read_b128 v[86:89], v186 offset:2048
	ds_read_b128 v[74:77], v185 offset:4096
	ds_read_b128 v[78:81], v186 offset:4096
	ds_read_b128 v[66:69], v185 offset:6144
	ds_read_b128 v[70:73], v186 offset:6144
	s_waitcnt lgkmcnt(8)
	v_mfma_scale_f32_32x32x64_f8f6f4 v[98:113], v[222:229], v[130:137], v[98:113], v194, v193 op_sel_hi:[0,0,0]
	v_mov_b32_e32 v0, v219
	s_nop 1
	v_permlane32_swap_b32_e32 v219, v0
	v_add_f32_e32 v219, v219, v0
	v_fma_f32 v209, v209, v218, v219
	v_max_f32_e32 v177, v114, v115
	v_max3_f32 v177, v177, v116, v117
	v_max3_f32 v177, v177, v118, v119
	v_max3_f32 v177, v177, v120, v121
	v_max3_f32 v177, v177, v122, v123
	v_max3_f32 v177, v177, v124, v125
	v_max3_f32 v177, v177, v126, v127
	v_max3_f32 v177, v177, v128, v129
	s_waitcnt vmcnt(0)
	ds_write_b128 v210, v[158:161] offset:43008
	ds_write_b128 v211, v[162:165] offset:51200
	s_waitcnt lgkmcnt(8)
	v_mfma_scale_f32_32x32x64_f8f6f4 v[50:65], v[246:253], v[90:97], v[50:65], v194, v194 op_sel_hi:[0,0,0]
	s_waitcnt lgkmcnt(6)
	v_mfma_scale_f32_32x32x64_f8f6f4 v[34:49], v[246:253], v[82:89], v[34:49], v194, v194 op_sel_hi:[0,0,0]
	s_waitcnt lgkmcnt(0)
	s_barrier
	global_load_dwordx4 v[158:161], v176, s[18:19]
	global_load_dwordx4 v[162:165], v178, s[16:17]
	v_add_u32_e32 v176, 0x2000, v176
	v_add_u32_e32 v178, 0x20000, v178
	s_waitcnt lgkmcnt(2)
	v_mfma_scale_f32_32x32x64_f8f6f4 v[18:33], v[246:253], v[74:81], v[18:33], v194, v194 op_sel_hi:[0,0,0]
	s_waitcnt lgkmcnt(0)
	v_mfma_scale_f32_32x32x64_f8f6f4 v[2:17], v[246:253], v[66:73], v[2:17], v194, v194 op_sel_hi:[0,0,0]
	v_max_f32_e32 v0, v98, v99
	v_max3_f32 v0, v0, v100, v101
	v_max3_f32 v0, v0, v102, v103
	v_max3_f32 v0, v0, v104, v105
	v_max3_f32 v0, v0, v106, v107
	v_max3_f32 v0, v0, v108, v109
	v_max3_f32 v0, v0, v110, v111
	v_max3_f32 v0, v0, v112, v113
	v_max_f32_e32 v177, v177, v0
	v_mov_b32_e32 v0, v177
	v_mov_b32_e32 v221, 1.0
	s_nop 0
	v_permlane32_swap_b32_e32 v177, v0
	v_max_f32_e32 v177, v177, v0
	v_cmp_ge_f32_e32 vcc, s90, v177
	s_cmp_eq_u64 vcc, exec
	s_cbranch_scc0 .Lmla_s0_newmax
; __device__ __forceinline__ void finishSM9(f32x16& p0, f32x16& p1, float alpha, float& l_reg, v8i32& p8) {
; #pragma unroll
;   for (int r = 0; r < 16; ++r) { p0[r] = __builtin_amdgcn_exp2f(p0[r]); p1[r] = __builtin_amdgcn_exp2f(p1[r]); }
;   float ps = 0;
; #pragma unroll
;   for (int r = 0; r < 16; ++r) ps += p0[r];
; #pragma unroll
;   for (int r = 0; r < 16; ++r) ps += p1[r];
;   { auto rr = __builtin_amdgcn_permlane32_swap(__float_as_uint(ps), __float_as_uint(ps), false, false);
;     ps = __uint_as_float(rr[0]) + __uint_as_float(rr[1]); }
;   l_reg = l_reg * alpha + ps;
; #pragma unroll
;   for (int g = 0; g < 4; ++g) {
;     int w = __builtin_amdgcn_cvt_pk_fp8_f32(p0[4 * g], p0[4 * g + 1], 0, false); p8[g] = __builtin_amdgcn_cvt_pk_fp8_f32(p0[4 * g + 2], p0[4 * g + 3], w, true);
;     int u = __builtin_amdgcn_cvt_pk_fp8_f32(p1[4 * g], p1[4 * g + 1], 0, false); p8[4 + g] = __builtin_amdgcn_cvt_pk_fp8_f32(p1[4 * g + 2], p1[4 * g + 3], u, true); }
; }
; __device__ __forceinline__ void pv8(f32x16* o, const char* Vt, const v8i32 p8, int r32, int hi) {
;   const int sw = (r32 >> 2) & 3, a0 = r32 * 64 + (((hi * 2) ^ sw) << 4), a1 = r32 * 64 + (((hi * 2 + 1) ^ sw) << 4);
; #pragma unroll
;   for (int d0 = 0; d0 < 4; ++d0) {
;     const v8i32 vf = cat8(*reinterpret_cast<const v4i32*>(Vt + d0 * 2048 + a0), *reinterpret_cast<const v4i32*>(Vt + d0 * 2048 + a1));
;     o[d0] = __builtin_amdgcn_mfma_scale_f32_32x32x64_f8f6f4(p8, vf, o[d0], 0, 0, 0, 127, 0, 127); }
; }
; __device__ __forceinline__ void qkt9(f32x16& p0, f32x16& p1, const char* Kn, const char* Kr, const v8i32* qf, const float init, int r32, int hi) {
; #pragma unroll
;   for (int r = 0; r < 16; ++r) { p0[r] = init; p1[r] = init; }
; #pragma unroll
;   for (int s = 0; s < 2; ++s) { const int c0 = s * 4 + hi * 2;
;     const v8i32 a0 = cat8(*reinterpret_cast<const v4i32*>(Kn + KN8SW(r32, c0)), *reinterpret_cast<const v4i32*>(Kn + KN8SW(r32, c0 + 1)));
;     const v8i32 a1 = cat8(*reinterpret_cast<const v4i32*>(Kn + 4096 + KN8SW(r32, c0)), *reinterpret_cast<const v4i32*>(Kn + 4096 + KN8SW(r32, c0 + 1)));
;     p0 = __builtin_amdgcn_mfma_scale_f32_32x32x64_f8f6f4(a0, qf[s], p0, 0, 0, 0, 127, 0, 124);
;     p1 = __builtin_amdgcn_mfma_scale_f32_32x32x64_f8f6f4(a1, qf[s], p1, 0, 0, 0, 127, 0, 124); }
;   { const int c0 = hi * 2;
.Lmla_s0_cont:
	ds_read_b128 v[82:85], v215 offset:51200
	ds_read_b128 v[86:89], v216 offset:51200
	ds_read_b128 v[222:225], v215 offset:55296
	ds_read_b128 v[226:229], v216 offset:55296
	v_exp_f32_e32 v0, v114
	v_exp_f32_e32 v177, v115
	v_exp_f32_e32 v179, v116
	v_exp_f32_e32 v254, v117
	v_add_f32_e32 v219, v0, v177
	v_cvt_pk_fp8_f32 v246, v0, v177
	v_add_f32_e32 v219, v179, v219
	v_add_f32_e32 v219, v254, v219
	v_cvt_pk_fp8_f32 v246, v179, v254 op_sel:[0,0,1]
	s_waitcnt lgkmcnt(2)
	v_mfma_scale_f32_32x32x64_f8f6f4 v[82:97], v[82:89], v[146:153], v[230:245], v194, v193 op_sel_hi:[0,0,0]
	v_exp_f32_e32 v0, v118
	v_exp_f32_e32 v177, v119
	v_exp_f32_e32 v179, v120
	v_exp_f32_e32 v254, v121
	v_add_f32_e32 v219, v0, v219
	v_add_f32_e32 v219, v177, v219
	v_cvt_pk_fp8_f32 v247, v0, v177
	v_add_f32_e32 v219, v179, v219
	v_add_f32_e32 v219, v254, v219
	v_cvt_pk_fp8_f32 v247, v179, v254 op_sel:[0,0,1]
	ds_read_b128 v[114:117], v213 offset:51200
	ds_read_b128 v[118:121], v214 offset:51200
	s_waitcnt lgkmcnt(2)
	v_mfma_scale_f32_32x32x64_f8f6f4 v[66:81], v[222:229], v[146:153], v[230:245], v194, v193 op_sel_hi:[0,0,0]
	ds_read_b128 v[222:225], v213 offset:55296
	ds_read_b128 v[226:229], v214 offset:55296
	v_exp_f32_e32 v0, v122
	v_exp_f32_e32 v177, v123
	v_exp_f32_e32 v179, v124
	v_exp_f32_e32 v254, v125
	v_add_f32_e32 v219, v0, v219
	v_add_f32_e32 v219, v177, v219
	v_cvt_pk_fp8_f32 v248, v0, v177
	v_add_f32_e32 v219, v179, v219
	v_add_f32_e32 v219, v254, v219
	v_cvt_pk_fp8_f32 v248, v179, v254 op_sel:[0,0,1]
	v_exp_f32_e32 v0, v126
	v_exp_f32_e32 v177, v127
	v_exp_f32_e32 v179, v128
	v_exp_f32_e32 v254, v129
	v_add_f32_e32 v219, v0, v219
	v_add_f32_e32 v219, v177, v219
	v_cvt_pk_fp8_f32 v249, v0, v177
	v_add_f32_e32 v219, v179, v219
	v_add_f32_e32 v219, v254, v219
	v_cvt_pk_fp8_f32 v249, v179, v254 op_sel:[0,0,1]
	ds_read_b128 v[122:125], v185 offset:59392
	ds_read_b128 v[126:129], v186 offset:59392
	s_waitcnt lgkmcnt(4)
	v_mfma_scale_f32_32x32x64_f8f6f4 v[82:97], v[114:121], v[138:145], v[82:97], v194, v193 op_sel_hi:[0,0,0]
	v_exp_f32_e32 v0, v98
	v_exp_f32_e32 v177, v99
	v_exp_f32_e32 v179, v100
	v_exp_f32_e32 v254, v101
	v_add_f32_e32 v219, v0, v219
	v_add_f32_e32 v219, v177, v219
	v_cvt_pk_fp8_f32 v250, v0, v177
	v_add_f32_e32 v219, v179, v219
	v_add_f32_e32 v219, v254, v219
	v_cvt_pk_fp8_f32 v250, v179, v254 op_sel:[0,0,1]
	s_waitcnt lgkmcnt(2)
	v_mfma_scale_f32_32x32x64_f8f6f4 v[66:81], v[222:229], v[138:145], v[66:81], v194, v193 op_sel_hi:[0,0,0]
	ds_read_b128 v[222:225], v185 offset:61440
	ds_read_b128 v[226:229], v186 offset:61440
	v_exp_f32_e32 v0, v102
	v_exp_f32_e32 v177, v103
	v_exp_f32_e32 v179, v104
	v_exp_f32_e32 v254, v105
	v_add_f32_e32 v219, v0, v219
	v_add_f32_e32 v219, v177, v219
	v_cvt_pk_fp8_f32 v251, v0, v177
	v_add_f32_e32 v219, v179, v219
	v_add_f32_e32 v219, v254, v219
	v_cvt_pk_fp8_f32 v251, v179, v254 op_sel:[0,0,1]
	v_exp_f32_e32 v0, v106
	v_exp_f32_e32 v177, v107
	v_exp_f32_e32 v179, v108
	v_exp_f32_e32 v254, v109
	v_add_f32_e32 v219, v0, v219
	v_add_f32_e32 v219, v177, v219
	v_cvt_pk_fp8_f32 v252, v0, v177
	v_add_f32_e32 v219, v179, v219
	v_add_f32_e32 v219, v254, v219
	v_cvt_pk_fp8_f32 v252, v179, v254 op_sel:[0,0,1]
	s_waitcnt lgkmcnt(2)
	v_mfma_scale_f32_32x32x64_f8f6f4 v[82:97], v[122:129], v[130:137], v[82:97], v194, v193 op_sel_hi:[0,0,0]
	v_exp_f32_e32 v0, v110
	v_exp_f32_e32 v177, v111
	v_exp_f32_e32 v179, v112
	v_exp_f32_e32 v254, v113
	v_add_f32_e32 v219, v0, v219
	v_add_f32_e32 v219, v177, v219
	v_cvt_pk_fp8_f32 v253, v0, v177
	v_add_f32_e32 v219, v179, v219
	v_add_f32_e32 v219, v254, v219
	v_cvt_pk_fp8_f32 v253, v179, v254 op_sel:[0,0,1]
	ds_read_b128 v[122:125], v185 offset:8192
	ds_read_b128 v[126:129], v186 offset:8192
	ds_read_b128 v[114:117], v185 offset:10240
	ds_read_b128 v[118:121], v186 offset:10240
	ds_read_b128 v[106:109], v185 offset:12288
	ds_read_b128 v[110:113], v186 offset:12288
	ds_read_b128 v[98:101], v185 offset:14336
	ds_read_b128 v[102:105], v186 offset:14336
	s_waitcnt lgkmcnt(8)
	v_mfma_scale_f32_32x32x64_f8f6f4 v[66:81], v[222:229], v[130:137], v[66:81], v194, v193 op_sel_hi:[0,0,0]
	v_mov_b32_e32 v0, v219
	s_nop 1
	v_permlane32_swap_b32_e32 v219, v0
	v_add_f32_e32 v219, v219, v0
	v_fma_f32 v209, v209, v221, v219
	v_max_f32_e32 v177, v82, v83
	v_max3_f32 v177, v177, v84, v85
	v_max3_f32 v177, v177, v86, v87
	v_max3_f32 v177, v177, v88, v89
	v_max3_f32 v177, v177, v90, v91
	v_max3_f32 v177, v177, v92, v93
	v_max3_f32 v177, v177, v94, v95
	v_max3_f32 v177, v177, v96, v97
	s_waitcnt vmcnt(0)
	ds_write_b128 v210, v[158:161]
	ds_write_b128 v211, v[162:165] offset:16384
	s_waitcnt lgkmcnt(8)
	v_mfma_scale_f32_32x32x64_f8f6f4 v[50:65], v[246:253], v[122:129], v[50:65], v194, v194 op_sel_hi:[0,0,0]
	s_waitcnt lgkmcnt(6)
	v_mfma_scale_f32_32x32x64_f8f6f4 v[34:49], v[246:253], v[114:121], v[34:49], v194, v194 op_sel_hi:[0,0,0]
	s_waitcnt lgkmcnt(0)
	s_barrier
	global_load_dwordx4 v[158:161], v176, s[18:19]
	global_load_dwordx4 v[162:165], v178, s[16:17]
	v_add_u32_e32 v176, 0x2000, v176
	v_add_u32_e32 v178, 0x20000, v178
	s_waitcnt lgkmcnt(2)
	v_mfma_scale_f32_32x32x64_f8f6f4 v[18:33], v[246:253], v[106:113], v[18:33], v194, v194 op_sel_hi:[0,0,0]
	s_waitcnt lgkmcnt(0)
	v_mfma_scale_f32_32x32x64_f8f6f4 v[2:17], v[246:253], v[98:105], v[2:17], v194, v194 op_sel_hi:[0,0,0]
	v_max_f32_e32 v0, v66, v67
	v_max3_f32 v0, v0, v68, v69
	v_max3_f32 v0, v0, v70, v71
	v_max3_f32 v0, v0, v72, v73
	v_max3_f32 v0, v0, v74, v75
	v_max3_f32 v0, v0, v76, v77
	v_max3_f32 v0, v0, v78, v79
	v_max3_f32 v0, v0, v80, v81
	v_max_f32_e32 v177, v177, v0
	v_mov_b32_e32 v0, v177
	v_mov_b32_e32 v218, 1.0
	s_nop 0
	v_permlane32_swap_b32_e32 v177, v0
	v_max_f32_e32 v177, v177, v0
	v_cmp_ge_f32_e32 vcc, s90, v177
	s_cmp_eq_u64 vcc, exec
	s_cbranch_scc0 .Lmla_s1_newmax
; __device__ __forceinline__ void finishSM9(f32x16& p0, f32x16& p1, float alpha, float& l_reg, v8i32& p8) {
; #pragma unroll
;   for (int r = 0; r < 16; ++r) { p0[r] = __builtin_amdgcn_exp2f(p0[r]); p1[r] = __builtin_amdgcn_exp2f(p1[r]); }
;   float ps = 0;
; #pragma unroll
;   for (int r = 0; r < 16; ++r) ps += p0[r];
; #pragma unroll
;   for (int r = 0; r < 16; ++r) ps += p1[r];
;   { auto rr = __builtin_amdgcn_permlane32_swap(__float_as_uint(ps), __float_as_uint(ps), false, false);
;     ps = __uint_as_float(rr[0]) + __uint_as_float(rr[1]); }
;   l_reg = l_reg * alpha + ps;
; #pragma unroll
;   for (int g = 0; g < 4; ++g) {
;     int w = __builtin_amdgcn_cvt_pk_fp8_f32(p0[4 * g], p0[4 * g + 1], 0, false); p8[g] = __builtin_amdgcn_cvt_pk_fp8_f32(p0[4 * g + 2], p0[4 * g + 3], w, true);
;     int u = __builtin_amdgcn_cvt_pk_fp8_f32(p1[4 * g], p1[4 * g + 1], 0, false); p8[4 + g] = __builtin_amdgcn_cvt_pk_fp8_f32(p1[4 * g + 2], p1[4 * g + 3], u, true); }
; }
; __device__ __forceinline__ void pv8(f32x16* o, const char* Vt, const v8i32 p8, int r32, int hi) {
;   const int sw = (r32 >> 2) & 3, a0 = r32 * 64 + (((hi * 2) ^ sw) << 4), a1 = r32 * 64 + (((hi * 2 + 1) ^ sw) << 4);
; #pragma unroll
;   for (int d0 = 0; d0 < 4; ++d0) {
;     const v8i32 vf = cat8(*reinterpret_cast<const v4i32*>(Vt + d0 * 2048 + a0), *reinterpret_cast<const v4i32*>(Vt + d0 * 2048 + a1));
;     o[d0] = __builtin_amdgcn_mfma_scale_f32_32x32x64_f8f6f4(p8, vf, o[d0], 0, 0, 0, 127, 0, 127); }
; }
; __device__ __forceinline__ void qkt9(f32x16& p0, f32x16& p1, const char* Kn, const char* Kr, const v8i32* qf, const float init, int r32, int hi) {
; #pragma unroll
;   for (int r = 0; r < 16; ++r) { p0[r] = init; p1[r] = init; }
; #pragma unroll
;   for (int s = 0; s < 2; ++s) { const int c0 = s * 4 + hi * 2;
;     const v8i32 a0 = cat8(*reinterpret_cast<const v4i32*>(Kn + KN8SW(r32, c0)), *reinterpret_cast<const v4i32*>(Kn + KN8SW(r32, c0 + 1)));
;     const v8i32 a1 = cat8(*reinterpret_cast<const v4i32*>(Kn + 4096 + KN8SW(r32, c0)), *reinterpret_cast<const v4i32*>(Kn + 4096 + KN8SW(r32, c0 + 1)));
;     p0 = __builtin_amdgcn_mfma_scale_f32_32x32x64_f8f6f4(a0, qf[s], p0, 0, 0, 0, 127, 0, 124);
;     p1 = __builtin_amdgcn_mfma_scale_f32_32x32x64_f8f6f4(a1, qf[s], p1, 0, 0, 0, 127, 0, 124); }
;   { const int c0 = hi * 2;
.Lmla_s1_cont:
	ds_read_b128 v[114:117], v215 offset:16384
	ds_read_b128 v[118:121], v216 offset:16384
	ds_read_b128 v[222:225], v215 offset:20480
	ds_read_b128 v[226:229], v216 offset:20480
	v_exp_f32_e32 v0, v82
	v_exp_f32_e32 v177, v83
	v_exp_f32_e32 v179, v84
	v_exp_f32_e32 v254, v85
	v_add_f32_e32 v219, v0, v177
	v_cvt_pk_fp8_f32 v246, v0, v177
	v_add_f32_e32 v219, v179, v219
	v_add_f32_e32 v219, v254, v219
	v_cvt_pk_fp8_f32 v246, v179, v254 op_sel:[0,0,1]
	s_waitcnt lgkmcnt(2)
	v_mfma_scale_f32_32x32x64_f8f6f4 v[114:129], v[114:121], v[146:153], v[230:245], v194, v193 op_sel_hi:[0,0,0]
	v_exp_f32_e32 v0, v86
	v_exp_f32_e32 v177, v87
	v_exp_f32_e32 v179, v88
	v_exp_f32_e32 v254, v89
	v_add_f32_e32 v219, v0, v219
	v_add_f32_e32 v219, v177, v219
	v_cvt_pk_fp8_f32 v247, v0, v177
	v_add_f32_e32 v219, v179, v219
	v_add_f32_e32 v219, v254, v219
	v_cvt_pk_fp8_f32 v247, v179, v254 op_sel:[0,0,1]
	ds_read_b128 v[82:85], v213 offset:16384
	ds_read_b128 v[86:89], v214 offset:16384
	s_waitcnt lgkmcnt(2)
	v_mfma_scale_f32_32x32x64_f8f6f4 v[98:113], v[222:229], v[146:153], v[230:245], v194, v193 op_sel_hi:[0,0,0]
	ds_read_b128 v[222:225], v213 offset:20480
	ds_read_b128 v[226:229], v214 offset:20480
	v_exp_f32_e32 v0, v90
	v_exp_f32_e32 v177, v91
	v_exp_f32_e32 v179, v92
	v_exp_f32_e32 v254, v93
	v_add_f32_e32 v219, v0, v219
	v_add_f32_e32 v219, v177, v219
	v_cvt_pk_fp8_f32 v248, v0, v177
	v_add_f32_e32 v219, v179, v219
	v_add_f32_e32 v219, v254, v219
	v_cvt_pk_fp8_f32 v248, v179, v254 op_sel:[0,0,1]
	v_exp_f32_e32 v0, v94
	v_exp_f32_e32 v177, v95
	v_exp_f32_e32 v179, v96
	v_exp_f32_e32 v254, v97
	v_add_f32_e32 v219, v0, v219
	v_add_f32_e32 v219, v177, v219
	v_cvt_pk_fp8_f32 v249, v0, v177
	v_add_f32_e32 v219, v179, v219
	v_add_f32_e32 v219, v254, v219
	v_cvt_pk_fp8_f32 v249, v179, v254 op_sel:[0,0,1]
	ds_read_b128 v[90:93], v185 offset:32768
	ds_read_b128 v[94:97], v186 offset:32768
	s_waitcnt lgkmcnt(4)
	v_mfma_scale_f32_32x32x64_f8f6f4 v[114:129], v[82:89], v[138:145], v[114:129], v194, v193 op_sel_hi:[0,0,0]
	v_exp_f32_e32 v0, v66
	v_exp_f32_e32 v177, v67
	v_exp_f32_e32 v179, v68
	v_exp_f32_e32 v254, v69
	v_add_f32_e32 v219, v0, v219
	v_add_f32_e32 v219, v177, v219
	v_cvt_pk_fp8_f32 v250, v0, v177
	v_add_f32_e32 v219, v179, v219
	v_add_f32_e32 v219, v254, v219
	v_cvt_pk_fp8_f32 v250, v179, v254 op_sel:[0,0,1]
	s_waitcnt lgkmcnt(2)
	v_mfma_scale_f32_32x32x64_f8f6f4 v[98:113], v[222:229], v[138:145], v[98:113], v194, v193 op_sel_hi:[0,0,0]
	ds_read_b128 v[222:225], v185 offset:34816
	ds_read_b128 v[226:229], v186 offset:34816
	v_exp_f32_e32 v0, v70
	v_exp_f32_e32 v177, v71
	v_exp_f32_e32 v179, v72
	v_exp_f32_e32 v254, v73
	v_add_f32_e32 v219, v0, v219
	v_add_f32_e32 v219, v177, v219
	v_cvt_pk_fp8_f32 v251, v0, v177
	v_add_f32_e32 v219, v179, v219
	v_add_f32_e32 v219, v254, v219
	v_cvt_pk_fp8_f32 v251, v179, v254 op_sel:[0,0,1]
	v_exp_f32_e32 v0, v74
	v_exp_f32_e32 v177, v75
	v_exp_f32_e32 v179, v76
	v_exp_f32_e32 v254, v77
	v_add_f32_e32 v219, v0, v219
	v_add_f32_e32 v219, v177, v219
	v_cvt_pk_fp8_f32 v252, v0, v177
	v_add_f32_e32 v219, v179, v219
	v_add_f32_e32 v219, v254, v219
	v_cvt_pk_fp8_f32 v252, v179, v254 op_sel:[0,0,1]
	s_waitcnt lgkmcnt(2)
	v_mfma_scale_f32_32x32x64_f8f6f4 v[114:129], v[90:97], v[130:137], v[114:129], v194, v193 op_sel_hi:[0,0,0]
	v_exp_f32_e32 v0, v78
	v_exp_f32_e32 v177, v79
	v_exp_f32_e32 v179, v80
	v_exp_f32_e32 v254, v81
	v_add_f32_e32 v219, v0, v219
	v_add_f32_e32 v219, v177, v219
	v_cvt_pk_fp8_f32 v253, v0, v177
	v_add_f32_e32 v219, v179, v219
	v_add_f32_e32 v219, v254, v219
	v_cvt_pk_fp8_f32 v253, v179, v254 op_sel:[0,0,1]
	ds_read_b128 v[90:93], v185 offset:43008
	ds_read_b128 v[94:97], v186 offset:43008
	ds_read_b128 v[82:85], v185 offset:45056
	ds_read_b128 v[86:89], v186 offset:45056
	ds_read_b128 v[74:77], v185 offset:47104
	ds_read_b128 v[78:81], v186 offset:47104
	ds_read_b128 v[66:69], v185 offset:49152
	ds_read_b128 v[70:73], v186 offset:49152
	s_waitcnt lgkmcnt(8)
	v_mfma_scale_f32_32x32x64_f8f6f4 v[98:113], v[222:229], v[130:137], v[98:113], v194, v193 op_sel_hi:[0,0,0]
	v_mov_b32_e32 v0, v219
	s_nop 1
	v_permlane32_swap_b32_e32 v219, v0
	v_add_f32_e32 v219, v219, v0
	v_fma_f32 v209, v209, v218, v219
	v_max_f32_e32 v177, v114, v115
	v_max3_f32 v177, v177, v116, v117
	v_max3_f32 v177, v177, v118, v119
	v_max3_f32 v177, v177, v120, v121
	v_max3_f32 v177, v177, v122, v123
	v_max3_f32 v177, v177, v124, v125
	v_max3_f32 v177, v177, v126, v127
	v_max3_f32 v177, v177, v128, v129
	s_waitcnt vmcnt(0)
	ds_write_b128 v210, v[158:161] offset:8192
	ds_write_b128 v211, v[162:165] offset:24576
	s_waitcnt lgkmcnt(8)
	v_mfma_scale_f32_32x32x64_f8f6f4 v[50:65], v[246:253], v[90:97], v[50:65], v194, v194 op_sel_hi:[0,0,0]
	s_waitcnt lgkmcnt(6)
	v_mfma_scale_f32_32x32x64_f8f6f4 v[34:49], v[246:253], v[82:89], v[34:49], v194, v194 op_sel_hi:[0,0,0]
	s_waitcnt lgkmcnt(0)
	s_barrier
	global_load_dwordx4 v[158:161], v176, s[18:19]
	global_load_dwordx4 v[162:165], v178, s[16:17]
	v_add_u32_e32 v176, 0x2000, v176
	v_add_u32_e32 v178, 0x20000, v178
	s_waitcnt lgkmcnt(2)
	v_mfma_scale_f32_32x32x64_f8f6f4 v[18:33], v[246:253], v[74:81], v[18:33], v194, v194 op_sel_hi:[0,0,0]
	s_waitcnt lgkmcnt(0)
	v_mfma_scale_f32_32x32x64_f8f6f4 v[2:17], v[246:253], v[66:73], v[2:17], v194, v194 op_sel_hi:[0,0,0]
	v_max_f32_e32 v0, v98, v99
	v_max3_f32 v0, v0, v100, v101
	v_max3_f32 v0, v0, v102, v103
	v_max3_f32 v0, v0, v104, v105
	v_max3_f32 v0, v0, v106, v107
	v_max3_f32 v0, v0, v108, v109
	v_max3_f32 v0, v0, v110, v111
	v_max3_f32 v0, v0, v112, v113
	v_max_f32_e32 v177, v177, v0
	v_mov_b32_e32 v0, v177
	v_mov_b32_e32 v221, 1.0
	s_nop 0
	v_permlane32_swap_b32_e32 v177, v0
	v_max_f32_e32 v177, v177, v0
	v_cmp_ge_f32_e32 vcc, s90, v177
	s_cmp_eq_u64 vcc, exec
	s_cbranch_scc0 .Lmla_s2_newmax
; __device__ __forceinline__ void finishSM9(f32x16& p0, f32x16& p1, float alpha, float& l_reg, v8i32& p8) {
; #pragma unroll
;   for (int r = 0; r < 16; ++r) { p0[r] = __builtin_amdgcn_exp2f(p0[r]); p1[r] = __builtin_amdgcn_exp2f(p1[r]); }
;   float ps = 0;
; #pragma unroll
;   for (int r = 0; r < 16; ++r) ps += p0[r];
; #pragma unroll
;   for (int r = 0; r < 16; ++r) ps += p1[r];
;   { auto rr = __builtin_amdgcn_permlane32_swap(__float_as_uint(ps), __float_as_uint(ps), false, false);
;     ps = __uint_as_float(rr[0]) + __uint_as_float(rr[1]); }
;   l_reg = l_reg * alpha + ps;
; #pragma unroll
;   for (int g = 0; g < 4; ++g) {
;     int w = __builtin_amdgcn_cvt_pk_fp8_f32(p0[4 * g], p0[4 * g + 1], 0, false); p8[g] = __builtin_amdgcn_cvt_pk_fp8_f32(p0[4 * g + 2], p0[4 * g + 3], w, true);
;     int u = __builtin_amdgcn_cvt_pk_fp8_f32(p1[4 * g], p1[4 * g + 1], 0, false); p8[4 + g] = __builtin_amdgcn_cvt_pk_fp8_f32(p1[4 * g + 2], p1[4 * g + 3], u, true); }
; }
; __device__ __forceinline__ void pv8(f32x16* o, const char* Vt, const v8i32 p8, int r32, int hi) {
;   const int sw = (r32 >> 2) & 3, a0 = r32 * 64 + (((hi * 2) ^ sw) << 4), a1 = r32 * 64 + (((hi * 2 + 1) ^ sw) << 4);
; #pragma unroll
;   for (int d0 = 0; d0 < 4; ++d0) {
;     const v8i32 vf = cat8(*reinterpret_cast<const v4i32*>(Vt + d0 * 2048 + a0), *reinterpret_cast<const v4i32*>(Vt + d0 * 2048 + a1));
;     o[d0] = __builtin_amdgcn_mfma_scale_f32_32x32x64_f8f6f4(p8, vf, o[d0], 0, 0, 0, 127, 0, 127); }
; }
; __device__ __forceinline__ void qkt9(f32x16& p0, f32x16& p1, const char* Kn, const char* Kr, const v8i32* qf, const float init, int r32, int hi) {
; #pragma unroll
;   for (int r = 0; r < 16; ++r) { p0[r] = init; p1[r] = init; }
; #pragma unroll
;   for (int s = 0; s < 2; ++s) { const int c0 = s * 4 + hi * 2;
;     const v8i32 a0 = cat8(*reinterpret_cast<const v4i32*>(Kn + KN8SW(r32, c0)), *reinterpret_cast<const v4i32*>(Kn + KN8SW(r32, c0 + 1)));
;     const v8i32 a1 = cat8(*reinterpret_cast<const v4i32*>(Kn + 4096 + KN8SW(r32, c0)), *reinterpret_cast<const v4i32*>(Kn + 4096 + KN8SW(r32, c0 + 1)));
;     p0 = __builtin_amdgcn_mfma_scale_f32_32x32x64_f8f6f4(a0, qf[s], p0, 0, 0, 0, 127, 0, 124);
;     p1 = __builtin_amdgcn_mfma_scale_f32_32x32x64_f8f6f4(a1, qf[s], p1, 0, 0, 0, 127, 0, 124); }
;   { const int c0 = hi * 2;
.Lmla_s2_cont:
	ds_read_b128 v[82:85], v215 offset:24576
	ds_read_b128 v[86:89], v216 offset:24576
	ds_read_b128 v[222:225], v215 offset:28672
	ds_read_b128 v[226:229], v216 offset:28672
	v_exp_f32_e32 v0, v114
	v_exp_f32_e32 v177, v115
	v_exp_f32_e32 v179, v116
	v_exp_f32_e32 v254, v117
	v_add_f32_e32 v219, v0, v177
	v_cvt_pk_fp8_f32 v246, v0, v177
	v_add_f32_e32 v219, v179, v219
	v_add_f32_e32 v219, v254, v219
	v_cvt_pk_fp8_f32 v246, v179, v254 op_sel:[0,0,1]
	s_waitcnt lgkmcnt(2)
	v_mfma_scale_f32_32x32x64_f8f6f4 v[82:97], v[82:89], v[146:153], v[230:245], v194, v193 op_sel_hi:[0,0,0]
	v_exp_f32_e32 v0, v118
	v_exp_f32_e32 v177, v119
	v_exp_f32_e32 v179, v120
	v_exp_f32_e32 v254, v121
	v_add_f32_e32 v219, v0, v219
	v_add_f32_e32 v219, v177, v219
	v_cvt_pk_fp8_f32 v247, v0, v177
	v_add_f32_e32 v219, v179, v219
	v_add_f32_e32 v219, v254, v219
	v_cvt_pk_fp8_f32 v247, v179, v254 op_sel:[0,0,1]
	ds_read_b128 v[114:117], v213 offset:24576
	ds_read_b128 v[118:121], v214 offset:24576
	s_waitcnt lgkmcnt(2)
	v_mfma_scale_f32_32x32x64_f8f6f4 v[66:81], v[222:229], v[146:153], v[230:245], v194, v193 op_sel_hi:[0,0,0]
	ds_read_b128 v[222:225], v213 offset:28672
	ds_read_b128 v[226:229], v214 offset:28672
	v_exp_f32_e32 v0, v122
	v_exp_f32_e32 v177, v123
	v_exp_f32_e32 v179, v124
	v_exp_f32_e32 v254, v125
	v_add_f32_e32 v219, v0, v219
	v_add_f32_e32 v219, v177, v219
	v_cvt_pk_fp8_f32 v248, v0, v177
	v_add_f32_e32 v219, v179, v219
	v_add_f32_e32 v219, v254, v219
	v_cvt_pk_fp8_f32 v248, v179, v254 op_sel:[0,0,1]
	v_exp_f32_e32 v0, v126
	v_exp_f32_e32 v177, v127
	v_exp_f32_e32 v179, v128
	v_exp_f32_e32 v254, v129
	v_add_f32_e32 v219, v0, v219
	v_add_f32_e32 v219, v177, v219
	v_cvt_pk_fp8_f32 v249, v0, v177
	v_add_f32_e32 v219, v179, v219
	v_add_f32_e32 v219, v254, v219
	v_cvt_pk_fp8_f32 v249, v179, v254 op_sel:[0,0,1]
	ds_read_b128 v[122:125], v185 offset:36864
	ds_read_b128 v[126:129], v186 offset:36864
	s_waitcnt lgkmcnt(4)
	v_mfma_scale_f32_32x32x64_f8f6f4 v[82:97], v[114:121], v[138:145], v[82:97], v194, v193 op_sel_hi:[0,0,0]
	v_exp_f32_e32 v0, v98
	v_exp_f32_e32 v177, v99
	v_exp_f32_e32 v179, v100
	v_exp_f32_e32 v254, v101
	v_add_f32_e32 v219, v0, v219
	v_add_f32_e32 v219, v177, v219
	v_cvt_pk_fp8_f32 v250, v0, v177
	v_add_f32_e32 v219, v179, v219
	v_add_f32_e32 v219, v254, v219
	v_cvt_pk_fp8_f32 v250, v179, v254 op_sel:[0,0,1]
	s_waitcnt lgkmcnt(2)
	v_mfma_scale_f32_32x32x64_f8f6f4 v[66:81], v[222:229], v[138:145], v[66:81], v194, v193 op_sel_hi:[0,0,0]
	ds_read_b128 v[222:225], v185 offset:38912
	ds_read_b128 v[226:229], v186 offset:38912
	v_exp_f32_e32 v0, v102
	v_exp_f32_e32 v177, v103
	v_exp_f32_e32 v179, v104
	v_exp_f32_e32 v254, v105
	v_add_f32_e32 v219, v0, v219
	v_add_f32_e32 v219, v177, v219
	v_cvt_pk_fp8_f32 v251, v0, v177
	v_add_f32_e32 v219, v179, v219
	v_add_f32_e32 v219, v254, v219
	v_cvt_pk_fp8_f32 v251, v179, v254 op_sel:[0,0,1]
	v_exp_f32_e32 v0, v106
	v_exp_f32_e32 v177, v107
	v_exp_f32_e32 v179, v108
	v_exp_f32_e32 v254, v109
	v_add_f32_e32 v219, v0, v219
	v_add_f32_e32 v219, v177, v219
	v_cvt_pk_fp8_f32 v252, v0, v177
	v_add_f32_e32 v219, v179, v219
	v_add_f32_e32 v219, v254, v219
	v_cvt_pk_fp8_f32 v252, v179, v254 op_sel:[0,0,1]
	s_waitcnt lgkmcnt(2)
	v_mfma_scale_f32_32x32x64_f8f6f4 v[82:97], v[122:129], v[130:137], v[82:97], v194, v193 op_sel_hi:[0,0,0]
	v_exp_f32_e32 v0, v110
	v_exp_f32_e32 v177, v111
	v_exp_f32_e32 v179, v112
	v_exp_f32_e32 v254, v113
	v_add_f32_e32 v219, v0, v219
	v_add_f32_e32 v219, v177, v219
	v_cvt_pk_fp8_f32 v253, v0, v177
	v_add_f32_e32 v219, v179, v219
	v_add_f32_e32 v219, v254, v219
	v_cvt_pk_fp8_f32 v253, v179, v254 op_sel:[0,0,1]
	ds_read_b128 v[122:125], v185 offset:0
	ds_read_b128 v[126:129], v186 offset:0
	ds_read_b128 v[114:117], v185 offset:2048
	ds_read_b128 v[118:121], v186 offset:2048
	ds_read_b128 v[106:109], v185 offset:4096
	ds_read_b128 v[110:113], v186 offset:4096
	ds_read_b128 v[98:101], v185 offset:6144
	ds_read_b128 v[102:105], v186 offset:6144
	s_waitcnt lgkmcnt(8)
	v_mfma_scale_f32_32x32x64_f8f6f4 v[66:81], v[222:229], v[130:137], v[66:81], v194, v193 op_sel_hi:[0,0,0]
	v_mov_b32_e32 v0, v219
	s_nop 1
	v_permlane32_swap_b32_e32 v219, v0
	v_add_f32_e32 v219, v219, v0
	v_fma_f32 v209, v209, v221, v219
	v_max_f32_e32 v177, v82, v83
	v_max3_f32 v177, v177, v84, v85
	v_max3_f32 v177, v177, v86, v87
	v_max3_f32 v177, v177, v88, v89
	v_max3_f32 v177, v177, v90, v91
	v_max3_f32 v177, v177, v92, v93
	v_max3_f32 v177, v177, v94, v95
	v_max3_f32 v177, v177, v96, v97
	s_waitcnt vmcnt(0)
	ds_write_b128 v210, v[158:161] offset:43008
	ds_write_b128 v211, v[162:165] offset:51200
	s_waitcnt lgkmcnt(8)
	v_mfma_scale_f32_32x32x64_f8f6f4 v[50:65], v[246:253], v[122:129], v[50:65], v194, v194 op_sel_hi:[0,0,0]
	s_waitcnt lgkmcnt(6)
	v_mfma_scale_f32_32x32x64_f8f6f4 v[34:49], v[246:253], v[114:121], v[34:49], v194, v194 op_sel_hi:[0,0,0]
	s_waitcnt lgkmcnt(0)
	s_barrier
	global_load_dwordx4 v[158:161], v176, s[18:19]
	global_load_dwordx4 v[162:165], v178, s[16:17]
	v_add_u32_e32 v176, 0x2000, v176
	v_add_u32_e32 v178, 0x20000, v178
	s_waitcnt lgkmcnt(2)
	v_mfma_scale_f32_32x32x64_f8f6f4 v[18:33], v[246:253], v[106:113], v[18:33], v194, v194 op_sel_hi:[0,0,0]
	s_waitcnt lgkmcnt(0)
	v_mfma_scale_f32_32x32x64_f8f6f4 v[2:17], v[246:253], v[98:105], v[2:17], v194, v194 op_sel_hi:[0,0,0]
	v_max_f32_e32 v0, v66, v67
	v_max3_f32 v0, v0, v68, v69
	v_max3_f32 v0, v0, v70, v71
	v_max3_f32 v0, v0, v72, v73
	v_max3_f32 v0, v0, v74, v75
	v_max3_f32 v0, v0, v76, v77
	v_max3_f32 v0, v0, v78, v79
	v_max3_f32 v0, v0, v80, v81
	v_max_f32_e32 v177, v177, v0
	v_mov_b32_e32 v0, v177
	v_mov_b32_e32 v218, 1.0
	s_nop 0
	v_permlane32_swap_b32_e32 v177, v0
	v_max_f32_e32 v177, v177, v0
	v_cmp_ge_f32_e32 vcc, s90, v177
	s_cmp_eq_u64 vcc, exec
	s_cbranch_scc0 .Lmla_s3_newmax
; __device__ __forceinline__ void finishSM9(f32x16& p0, f32x16& p1, float alpha, float& l_reg, v8i32& p8) {
; #pragma unroll
;   for (int r = 0; r < 16; ++r) { p0[r] = __builtin_amdgcn_exp2f(p0[r]); p1[r] = __builtin_amdgcn_exp2f(p1[r]); }
;   float ps = 0;
; #pragma unroll
;   for (int r = 0; r < 16; ++r) ps += p0[r];
; #pragma unroll
;   for (int r = 0; r < 16; ++r) ps += p1[r];
;   { auto rr = __builtin_amdgcn_permlane32_swap(__float_as_uint(ps), __float_as_uint(ps), false, false);
;     ps = __uint_as_float(rr[0]) + __uint_as_float(rr[1]); }
;   l_reg = l_reg * alpha + ps;
; #pragma unroll
;   for (int g = 0; g < 4; ++g) {
;     int w = __builtin_amdgcn_cvt_pk_fp8_f32(p0[4 * g], p0[4 * g + 1], 0, false); p8[g] = __builtin_amdgcn_cvt_pk_fp8_f32(p0[4 * g + 2], p0[4 * g + 3], w, true);
;     int u = __builtin_amdgcn_cvt_pk_fp8_f32(p1[4 * g], p1[4 * g + 1], 0, false); p8[4 + g] = __builtin_amdgcn_cvt_pk_fp8_f32(p1[4 * g + 2], p1[4 * g + 3], u, true); }
; }
; __device__ __forceinline__ void pv8(f32x16* o, const char* Vt, const v8i32 p8, int r32, int hi) {
;   const int sw = (r32 >> 2) & 3, a0 = r32 * 64 + (((hi * 2) ^ sw) << 4), a1 = r32 * 64 + (((hi * 2 + 1) ^ sw) << 4);
; #pragma unroll
;   for (int d0 = 0; d0 < 4; ++d0) {
;     const v8i32 vf = cat8(*reinterpret_cast<const v4i32*>(Vt + d0 * 2048 + a0), *reinterpret_cast<const v4i32*>(Vt + d0 * 2048 + a1));
;     o[d0] = __builtin_amdgcn_mfma_scale_f32_32x32x64_f8f6f4(p8, vf, o[d0], 0, 0, 0, 127, 0, 127); }
; }
; __device__ __forceinline__ void qkt9(f32x16& p0, f32x16& p1, const char* Kn, const char* Kr, const v8i32* qf, const float init, int r32, int hi) {
; #pragma unroll
;   for (int r = 0; r < 16; ++r) { p0[r] = init; p1[r] = init; }
; #pragma unroll
;   for (int s = 0; s < 2; ++s) { const int c0 = s * 4 + hi * 2;
;     const v8i32 a0 = cat8(*reinterpret_cast<const v4i32*>(Kn + KN8SW(r32, c0)), *reinterpret_cast<const v4i32*>(Kn + KN8SW(r32, c0 + 1)));
;     const v8i32 a1 = cat8(*reinterpret_cast<const v4i32*>(Kn + 4096 + KN8SW(r32, c0)), *reinterpret_cast<const v4i32*>(Kn + 4096 + KN8SW(r32, c0 + 1)));
;     p0 = __builtin_amdgcn_mfma_scale_f32_32x32x64_f8f6f4(a0, qf[s], p0, 0, 0, 0, 127, 0, 124);
;     p1 = __builtin_amdgcn_mfma_scale_f32_32x32x64_f8f6f4(a1, qf[s], p1, 0, 0, 0, 127, 0, 124); }
;   { const int c0 = hi * 2;
.Lmla_s3_cont:
	ds_read_b128 v[114:117], v215 offset:51200
	ds_read_b128 v[118:121], v216 offset:51200
	ds_read_b128 v[222:225], v215 offset:55296
	ds_read_b128 v[226:229], v216 offset:55296
	v_exp_f32_e32 v0, v82
	v_exp_f32_e32 v177, v83
	v_exp_f32_e32 v179, v84
	v_exp_f32_e32 v254, v85
	v_add_f32_e32 v219, v0, v177
	v_cvt_pk_fp8_f32 v246, v0, v177
	v_add_f32_e32 v219, v179, v219
	v_add_f32_e32 v219, v254, v219
	v_cvt_pk_fp8_f32 v246, v179, v254 op_sel:[0,0,1]
	s_waitcnt lgkmcnt(2)
	v_mfma_scale_f32_32x32x64_f8f6f4 v[114:129], v[114:121], v[146:153], v[230:245], v194, v193 op_sel_hi:[0,0,0]
	v_exp_f32_e32 v0, v86
	v_exp_f32_e32 v177, v87
	v_exp_f32_e32 v179, v88
	v_exp_f32_e32 v254, v89
	v_add_f32_e32 v219, v0, v219
	v_add_f32_e32 v219, v177, v219
	v_cvt_pk_fp8_f32 v247, v0, v177
	v_add_f32_e32 v219, v179, v219
	v_add_f32_e32 v219, v254, v219
	v_cvt_pk_fp8_f32 v247, v179, v254 op_sel:[0,0,1]
	ds_read_b128 v[82:85], v213 offset:51200
	ds_read_b128 v[86:89], v214 offset:51200
	s_waitcnt lgkmcnt(2)
	v_mfma_scale_f32_32x32x64_f8f6f4 v[98:113], v[222:229], v[146:153], v[230:245], v194, v193 op_sel_hi:[0,0,0]
	ds_read_b128 v[222:225], v213 offset:55296
	ds_read_b128 v[226:229], v214 offset:55296
	v_exp_f32_e32 v0, v90
	v_exp_f32_e32 v177, v91
	v_exp_f32_e32 v179, v92
	v_exp_f32_e32 v254, v93
	v_add_f32_e32 v219, v0, v219
	v_add_f32_e32 v219, v177, v219
	v_cvt_pk_fp8_f32 v248, v0, v177
	v_add_f32_e32 v219, v179, v219
	v_add_f32_e32 v219, v254, v219
	v_cvt_pk_fp8_f32 v248, v179, v254 op_sel:[0,0,1]
	v_exp_f32_e32 v0, v94
	v_exp_f32_e32 v177, v95
	v_exp_f32_e32 v179, v96
	v_exp_f32_e32 v254, v97
	v_add_f32_e32 v219, v0, v219
	v_add_f32_e32 v219, v177, v219
	v_cvt_pk_fp8_f32 v249, v0, v177
	v_add_f32_e32 v219, v179, v219
	v_add_f32_e32 v219, v254, v219
	v_cvt_pk_fp8_f32 v249, v179, v254 op_sel:[0,0,1]
	ds_read_b128 v[90:93], v185 offset:59392
	ds_read_b128 v[94:97], v186 offset:59392
	s_waitcnt lgkmcnt(4)
	v_mfma_scale_f32_32x32x64_f8f6f4 v[114:129], v[82:89], v[138:145], v[114:129], v194, v193 op_sel_hi:[0,0,0]
	v_exp_f32_e32 v0, v66
	v_exp_f32_e32 v177, v67
	v_exp_f32_e32 v179, v68
	v_exp_f32_e32 v254, v69
	v_add_f32_e32 v219, v0, v219
	v_add_f32_e32 v219, v177, v219
	v_cvt_pk_fp8_f32 v250, v0, v177
	v_add_f32_e32 v219, v179, v219
	v_add_f32_e32 v219, v254, v219
	v_cvt_pk_fp8_f32 v250, v179, v254 op_sel:[0,0,1]
	s_waitcnt lgkmcnt(2)
	v_mfma_scale_f32_32x32x64_f8f6f4 v[98:113], v[222:229], v[138:145], v[98:113], v194, v193 op_sel_hi:[0,0,0]
	ds_read_b128 v[222:225], v185 offset:61440
	ds_read_b128 v[226:229], v186 offset:61440
	v_exp_f32_e32 v0, v70
	v_exp_f32_e32 v177, v71
	v_exp_f32_e32 v179, v72
	v_exp_f32_e32 v254, v73
	v_add_f32_e32 v219, v0, v219
	v_add_f32_e32 v219, v177, v219
	v_cvt_pk_fp8_f32 v251, v0, v177
	v_add_f32_e32 v219, v179, v219
	v_add_f32_e32 v219, v254, v219
	v_cvt_pk_fp8_f32 v251, v179, v254 op_sel:[0,0,1]
	v_exp_f32_e32 v0, v74
	v_exp_f32_e32 v177, v75
	v_exp_f32_e32 v179, v76
	v_exp_f32_e32 v254, v77
	v_add_f32_e32 v219, v0, v219
	v_add_f32_e32 v219, v177, v219
	v_cvt_pk_fp8_f32 v252, v0, v177
	v_add_f32_e32 v219, v179, v219
	v_add_f32_e32 v219, v254, v219
	v_cvt_pk_fp8_f32 v252, v179, v254 op_sel:[0,0,1]
	s_waitcnt lgkmcnt(2)
	v_mfma_scale_f32_32x32x64_f8f6f4 v[114:129], v[90:97], v[130:137], v[114:129], v194, v193 op_sel_hi:[0,0,0]
	v_exp_f32_e32 v0, v78
	v_exp_f32_e32 v177, v79
	v_exp_f32_e32 v179, v80
	v_exp_f32_e32 v254, v81
	v_add_f32_e32 v219, v0, v219
	v_add_f32_e32 v219, v177, v219
	v_cvt_pk_fp8_f32 v253, v0, v177
	v_add_f32_e32 v219, v179, v219
	v_add_f32_e32 v219, v254, v219
	v_cvt_pk_fp8_f32 v253, v179, v254 op_sel:[0,0,1]
	ds_read_b128 v[90:93], v185 offset:8192
	ds_read_b128 v[94:97], v186 offset:8192
	ds_read_b128 v[82:85], v185 offset:10240
	ds_read_b128 v[86:89], v186 offset:10240
	ds_read_b128 v[74:77], v185 offset:12288
	ds_read_b128 v[78:81], v186 offset:12288
	ds_read_b128 v[66:69], v185 offset:14336
	ds_read_b128 v[70:73], v186 offset:14336
	s_waitcnt lgkmcnt(8)
	v_mfma_scale_f32_32x32x64_f8f6f4 v[98:113], v[222:229], v[130:137], v[98:113], v194, v193 op_sel_hi:[0,0,0]
	v_mov_b32_e32 v0, v219
	s_nop 1
	v_permlane32_swap_b32_e32 v219, v0
	v_add_f32_e32 v219, v219, v0
	v_fma_f32 v209, v209, v218, v219
	v_max_f32_e32 v177, v114, v115
	v_max3_f32 v177, v177, v116, v117
	v_max3_f32 v177, v177, v118, v119
	v_max3_f32 v177, v177, v120, v121
	v_max3_f32 v177, v177, v122, v123
	v_max3_f32 v177, v177, v124, v125
	v_max3_f32 v177, v177, v126, v127
	v_max3_f32 v177, v177, v128, v129
	s_waitcnt vmcnt(0)
	ds_write_b128 v210, v[158:161]
	ds_write_b128 v211, v[162:165] offset:16384
	s_waitcnt lgkmcnt(8)
	v_mfma_scale_f32_32x32x64_f8f6f4 v[50:65], v[246:253], v[90:97], v[50:65], v194, v194 op_sel_hi:[0,0,0]
	s_waitcnt lgkmcnt(6)
	v_mfma_scale_f32_32x32x64_f8f6f4 v[34:49], v[246:253], v[82:89], v[34:49], v194, v194 op_sel_hi:[0,0,0]
	s_waitcnt lgkmcnt(0)
	s_barrier
	global_load_dwordx4 v[158:161], v176, s[18:19]
	global_load_dwordx4 v[162:165], v178, s[16:17]
	v_add_u32_e32 v176, 0x2000, v176
	v_add_u32_e32 v178, 0x20000, v178
	s_waitcnt lgkmcnt(2)
	v_mfma_scale_f32_32x32x64_f8f6f4 v[18:33], v[246:253], v[74:81], v[18:33], v194, v194 op_sel_hi:[0,0,0]
	s_waitcnt lgkmcnt(0)
	v_mfma_scale_f32_32x32x64_f8f6f4 v[2:17], v[246:253], v[66:73], v[2:17], v194, v194 op_sel_hi:[0,0,0]
	v_max_f32_e32 v0, v98, v99
	v_max3_f32 v0, v0, v100, v101
	v_max3_f32 v0, v0, v102, v103
	v_max3_f32 v0, v0, v104, v105
	v_max3_f32 v0, v0, v106, v107
	v_max3_f32 v0, v0, v108, v109
	v_max3_f32 v0, v0, v110, v111
	v_max3_f32 v0, v0, v112, v113
	v_max_f32_e32 v177, v177, v0
	v_mov_b32_e32 v0, v177
	v_mov_b32_e32 v221, 1.0
	s_nop 0
	v_permlane32_swap_b32_e32 v177, v0
	v_max_f32_e32 v177, v177, v0
	v_cmp_ge_f32_e32 vcc, s90, v177
	s_cmp_eq_u64 vcc, exec
	s_cbranch_scc0 .Lmla_s4_newmax
; __device__ __forceinline__ void finishSM9(f32x16& p0, f32x16& p1, float alpha, float& l_reg, v8i32& p8) {
; #pragma unroll
;   for (int r = 0; r < 16; ++r) { p0[r] = __builtin_amdgcn_exp2f(p0[r]); p1[r] = __builtin_amdgcn_exp2f(p1[r]); }
;   float ps = 0;
; #pragma unroll
;   for (int r = 0; r < 16; ++r) ps += p0[r];
; #pragma unroll
;   for (int r = 0; r < 16; ++r) ps += p1[r];
;   { auto rr = __builtin_amdgcn_permlane32_swap(__float_as_uint(ps), __float_as_uint(ps), false, false);
;     ps = __uint_as_float(rr[0]) + __uint_as_float(rr[1]); }
;   l_reg = l_reg * alpha + ps;
; #pragma unroll
;   for (int g = 0; g < 4; ++g) {
;     int w = __builtin_amdgcn_cvt_pk_fp8_f32(p0[4 * g], p0[4 * g + 1], 0, false); p8[g] = __builtin_amdgcn_cvt_pk_fp8_f32(p0[4 * g + 2], p0[4 * g + 3], w, true);
;     int u = __builtin_amdgcn_cvt_pk_fp8_f32(p1[4 * g], p1[4 * g + 1], 0, false); p8[4 + g] = __builtin_amdgcn_cvt_pk_fp8_f32(p1[4 * g + 2], p1[4 * g + 3], u, true); }
; }
; __device__ __forceinline__ void pv8(f32x16* o, const char* Vt, const v8i32 p8, int r32, int hi) {
;   const int sw = (r32 >> 2) & 3, a0 = r32 * 64 + (((hi * 2) ^ sw) << 4), a1 = r32 * 64 + (((hi * 2 + 1) ^ sw) << 4);
; #pragma unroll
;   for (int d0 = 0; d0 < 4; ++d0) {
;     const v8i32 vf = cat8(*reinterpret_cast<const v4i32*>(Vt + d0 * 2048 + a0), *reinterpret_cast<const v4i32*>(Vt + d0 * 2048 + a1));
;     o[d0] = __builtin_amdgcn_mfma_scale_f32_32x32x64_f8f6f4(p8, vf, o[d0], 0, 0, 0, 127, 0, 127); }
; }
; __device__ __forceinline__ void qkt9(f32x16& p0, f32x16& p1, const char* Kn, const char* Kr, const v8i32* qf, const float init, int r32, int hi) {
; #pragma unroll
;   for (int r = 0; r < 16; ++r) { p0[r] = init; p1[r] = init; }
; #pragma unroll
;   for (int s = 0; s < 2; ++s) { const int c0 = s * 4 + hi * 2;
;     const v8i32 a0 = cat8(*reinterpret_cast<const v4i32*>(Kn + KN8SW(r32, c0)), *reinterpret_cast<const v4i32*>(Kn + KN8SW(r32, c0 + 1)));
;     const v8i32 a1 = cat8(*reinterpret_cast<const v4i32*>(Kn + 4096 + KN8SW(r32, c0)), *reinterpret_cast<const v4i32*>(Kn + 4096 + KN8SW(r32, c0 + 1)));
;     p0 = __builtin_amdgcn_mfma_scale_f32_32x32x64_f8f6f4(a0, qf[s], p0, 0, 0, 0, 127, 0, 124);
;     p1 = __builtin_amdgcn_mfma_scale_f32_32x32x64_f8f6f4(a1, qf[s], p1, 0, 0, 0, 127, 0, 124); }
;   { const int c0 = hi * 2;
.Lmla_s4_cont:
	ds_read_b128 v[82:85], v215 offset:16384
	ds_read_b128 v[86:89], v216 offset:16384
	ds_read_b128 v[222:225], v215 offset:20480
	ds_read_b128 v[226:229], v216 offset:20480
	v_exp_f32_e32 v0, v114
	v_exp_f32_e32 v177, v115
	v_exp_f32_e32 v179, v116
	v_exp_f32_e32 v254, v117
	v_add_f32_e32 v219, v0, v177
	v_cvt_pk_fp8_f32 v246, v0, v177
	v_add_f32_e32 v219, v179, v219
	v_add_f32_e32 v219, v254, v219
	v_cvt_pk_fp8_f32 v246, v179, v254 op_sel:[0,0,1]
	s_waitcnt lgkmcnt(2)
	v_mfma_scale_f32_32x32x64_f8f6f4 v[82:97], v[82:89], v[146:153], v[230:245], v194, v193 op_sel_hi:[0,0,0]
	v_exp_f32_e32 v0, v118
	v_exp_f32_e32 v177, v119
	v_exp_f32_e32 v179, v120
	v_exp_f32_e32 v254, v121
	v_add_f32_e32 v219, v0, v219
	v_add_f32_e32 v219, v177, v219
	v_cvt_pk_fp8_f32 v247, v0, v177
	v_add_f32_e32 v219, v179, v219
	v_add_f32_e32 v219, v254, v219
	v_cvt_pk_fp8_f32 v247, v179, v254 op_sel:[0,0,1]
	ds_read_b128 v[114:117], v213 offset:16384
	ds_read_b128 v[118:121], v214 offset:16384
	s_waitcnt lgkmcnt(2)
	v_mfma_scale_f32_32x32x64_f8f6f4 v[66:81], v[222:229], v[146:153], v[230:245], v194, v193 op_sel_hi:[0,0,0]
	ds_read_b128 v[222:225], v213 offset:20480
	ds_read_b128 v[226:229], v214 offset:20480
	v_exp_f32_e32 v0, v122
	v_exp_f32_e32 v177, v123
	v_exp_f32_e32 v179, v124
	v_exp_f32_e32 v254, v125
	v_add_f32_e32 v219, v0, v219
	v_add_f32_e32 v219, v177, v219
	v_cvt_pk_fp8_f32 v248, v0, v177
	v_add_f32_e32 v219, v179, v219
	v_add_f32_e32 v219, v254, v219
	v_cvt_pk_fp8_f32 v248, v179, v254 op_sel:[0,0,1]
	v_exp_f32_e32 v0, v126
	v_exp_f32_e32 v177, v127
	v_exp_f32_e32 v179, v128
	v_exp_f32_e32 v254, v129
	v_add_f32_e32 v219, v0, v219
	v_add_f32_e32 v219, v177, v219
	v_cvt_pk_fp8_f32 v249, v0, v177
	v_add_f32_e32 v219, v179, v219
	v_add_f32_e32 v219, v254, v219
	v_cvt_pk_fp8_f32 v249, v179, v254 op_sel:[0,0,1]
	ds_read_b128 v[122:125], v185 offset:32768
	ds_read_b128 v[126:129], v186 offset:32768
	s_waitcnt lgkmcnt(4)
	v_mfma_scale_f32_32x32x64_f8f6f4 v[82:97], v[114:121], v[138:145], v[82:97], v194, v193 op_sel_hi:[0,0,0]
	v_exp_f32_e32 v0, v98
	v_exp_f32_e32 v177, v99
	v_exp_f32_e32 v179, v100
	v_exp_f32_e32 v254, v101
	v_add_f32_e32 v219, v0, v219
	v_add_f32_e32 v219, v177, v219
	v_cvt_pk_fp8_f32 v250, v0, v177
	v_add_f32_e32 v219, v179, v219
	v_add_f32_e32 v219, v254, v219
	v_cvt_pk_fp8_f32 v250, v179, v254 op_sel:[0,0,1]
	s_waitcnt lgkmcnt(2)
	v_mfma_scale_f32_32x32x64_f8f6f4 v[66:81], v[222:229], v[138:145], v[66:81], v194, v193 op_sel_hi:[0,0,0]
	ds_read_b128 v[222:225], v185 offset:34816
	ds_read_b128 v[226:229], v186 offset:34816
	v_exp_f32_e32 v0, v102
	v_exp_f32_e32 v177, v103
	v_exp_f32_e32 v179, v104
	v_exp_f32_e32 v254, v105
	v_add_f32_e32 v219, v0, v219
	v_add_f32_e32 v219, v177, v219
	v_cvt_pk_fp8_f32 v251, v0, v177
	v_add_f32_e32 v219, v179, v219
	v_add_f32_e32 v219, v254, v219
	v_cvt_pk_fp8_f32 v251, v179, v254 op_sel:[0,0,1]
	v_exp_f32_e32 v0, v106
	v_exp_f32_e32 v177, v107
	v_exp_f32_e32 v179, v108
	v_exp_f32_e32 v254, v109
	v_add_f32_e32 v219, v0, v219
	v_add_f32_e32 v219, v177, v219
	v_cvt_pk_fp8_f32 v252, v0, v177
	v_add_f32_e32 v219, v179, v219
	v_add_f32_e32 v219, v254, v219
	v_cvt_pk_fp8_f32 v252, v179, v254 op_sel:[0,0,1]
	s_waitcnt lgkmcnt(2)
	v_mfma_scale_f32_32x32x64_f8f6f4 v[82:97], v[122:129], v[130:137], v[82:97], v194, v193 op_sel_hi:[0,0,0]
	v_exp_f32_e32 v0, v110
	v_exp_f32_e32 v177, v111
	v_exp_f32_e32 v179, v112
	v_exp_f32_e32 v254, v113
	v_add_f32_e32 v219, v0, v219
	v_add_f32_e32 v219, v177, v219
	v_cvt_pk_fp8_f32 v253, v0, v177
	v_add_f32_e32 v219, v179, v219
	v_add_f32_e32 v219, v254, v219
	v_cvt_pk_fp8_f32 v253, v179, v254 op_sel:[0,0,1]
	ds_read_b128 v[122:125], v185 offset:43008
	ds_read_b128 v[126:129], v186 offset:43008
	ds_read_b128 v[114:117], v185 offset:45056
	ds_read_b128 v[118:121], v186 offset:45056
	ds_read_b128 v[106:109], v185 offset:47104
	ds_read_b128 v[110:113], v186 offset:47104
	ds_read_b128 v[98:101], v185 offset:49152
	ds_read_b128 v[102:105], v186 offset:49152
	s_waitcnt lgkmcnt(8)
	v_mfma_scale_f32_32x32x64_f8f6f4 v[66:81], v[222:229], v[130:137], v[66:81], v194, v193 op_sel_hi:[0,0,0]
	v_mov_b32_e32 v0, v219
	s_nop 1
	v_permlane32_swap_b32_e32 v219, v0
	v_add_f32_e32 v219, v219, v0
	v_fma_f32 v209, v209, v221, v219
	v_max_f32_e32 v177, v82, v83
	v_max3_f32 v177, v177, v84, v85
	v_max3_f32 v177, v177, v86, v87
	v_max3_f32 v177, v177, v88, v89
	v_max3_f32 v177, v177, v90, v91
	v_max3_f32 v177, v177, v92, v93
	v_max3_f32 v177, v177, v94, v95
	v_max3_f32 v177, v177, v96, v97
	s_waitcnt vmcnt(0)
	ds_write_b128 v210, v[158:161] offset:8192
	ds_write_b128 v211, v[162:165] offset:24576
	s_waitcnt lgkmcnt(8)
	v_mfma_scale_f32_32x32x64_f8f6f4 v[50:65], v[246:253], v[122:129], v[50:65], v194, v194 op_sel_hi:[0,0,0]
	s_waitcnt lgkmcnt(6)
	v_mfma_scale_f32_32x32x64_f8f6f4 v[34:49], v[246:253], v[114:121], v[34:49], v194, v194 op_sel_hi:[0,0,0]
	s_waitcnt lgkmcnt(0)
	s_barrier
	global_load_dwordx4 v[158:161], v176, s[18:19]
	global_load_dwordx4 v[162:165], v178, s[16:17]
	v_add_u32_e32 v176, 0x2000, v176
	v_add_u32_e32 v178, 0x20000, v178
	s_waitcnt lgkmcnt(2)
	v_mfma_scale_f32_32x32x64_f8f6f4 v[18:33], v[246:253], v[106:113], v[18:33], v194, v194 op_sel_hi:[0,0,0]
	s_waitcnt lgkmcnt(0)
	v_mfma_scale_f32_32x32x64_f8f6f4 v[2:17], v[246:253], v[98:105], v[2:17], v194, v194 op_sel_hi:[0,0,0]
	v_max_f32_e32 v0, v66, v67
	v_max3_f32 v0, v0, v68, v69
	v_max3_f32 v0, v0, v70, v71
	v_max3_f32 v0, v0, v72, v73
	v_max3_f32 v0, v0, v74, v75
	v_max3_f32 v0, v0, v76, v77
	v_max3_f32 v0, v0, v78, v79
	v_max3_f32 v0, v0, v80, v81
	v_max_f32_e32 v177, v177, v0
	v_mov_b32_e32 v0, v177
	v_mov_b32_e32 v218, 1.0
	s_nop 0
	v_permlane32_swap_b32_e32 v177, v0
	v_max_f32_e32 v177, v177, v0
	v_cmp_ge_f32_e32 vcc, s90, v177
	s_cmp_eq_u64 vcc, exec
	s_cbranch_scc0 .Lmla_s5_newmax
; __device__ __forceinline__ void finishSM9(f32x16& p0, f32x16& p1, float alpha, float& l_reg, v8i32& p8) {
; #pragma unroll
;   for (int r = 0; r < 16; ++r) { p0[r] = __builtin_amdgcn_exp2f(p0[r]); p1[r] = __builtin_amdgcn_exp2f(p1[r]); }
;   float ps = 0;
; #pragma unroll
;   for (int r = 0; r < 16; ++r) ps += p0[r];
; #pragma unroll
;   for (int r = 0; r < 16; ++r) ps += p1[r];
;   { auto rr = __builtin_amdgcn_permlane32_swap(__float_as_uint(ps), __float_as_uint(ps), false, false);
;     ps = __uint_as_float(rr[0]) + __uint_as_float(rr[1]); }
;   l_reg = l_reg * alpha + ps;
; #pragma unroll
;   for (int g = 0; g < 4; ++g) {
;     int w = __builtin_amdgcn_cvt_pk_fp8_f32(p0[4 * g], p0[4 * g + 1], 0, false); p8[g] = __builtin_amdgcn_cvt_pk_fp8_f32(p0[4 * g + 2], p0[4 * g + 3], w, true);
;     int u = __builtin_amdgcn_cvt_pk_fp8_f32(p1[4 * g], p1[4 * g + 1], 0, false); p8[4 + g] = __builtin_amdgcn_cvt_pk_fp8_f32(p1[4 * g + 2], p1[4 * g + 3], u, true); }
; }
; __device__ __forceinline__ void pv8(f32x16* o, const char* Vt, const v8i32 p8, int r32, int hi) {
;   const int sw = (r32 >> 2) & 3, a0 = r32 * 64 + (((hi * 2) ^ sw) << 4), a1 = r32 * 64 + (((hi * 2 + 1) ^ sw) << 4);
; #pragma unroll
;   for (int d0 = 0; d0 < 4; ++d0) {
;     const v8i32 vf = cat8(*reinterpret_cast<const v4i32*>(Vt + d0 * 2048 + a0), *reinterpret_cast<const v4i32*>(Vt + d0 * 2048 + a1));
;     o[d0] = __builtin_amdgcn_mfma_scale_f32_32x32x64_f8f6f4(p8, vf, o[d0], 0, 0, 0, 127, 0, 127); }
; }
; __device__ __forceinline__ void qkt9(f32x16& p0, f32x16& p1, const char* Kn, const char* Kr, const v8i32* qf, const float init, int r32, int hi) {
; #pragma unroll
;   for (int r = 0; r < 16; ++r) { p0[r] = init; p1[r] = init; }
; #pragma unroll
;   for (int s = 0; s < 2; ++s) { const int c0 = s * 4 + hi * 2;
;     const v8i32 a0 = cat8(*reinterpret_cast<const v4i32*>(Kn + KN8SW(r32, c0)), *reinterpret_cast<const v4i32*>(Kn + KN8SW(r32, c0 + 1)));
;     const v8i32 a1 = cat8(*reinterpret_cast<const v4i32*>(Kn + 4096 + KN8SW(r32, c0)), *reinterpret_cast<const v4i32*>(Kn + 4096 + KN8SW(r32, c0 + 1)));
;     p0 = __builtin_amdgcn_mfma_scale_f32_32x32x64_f8f6f4(a0, qf[s], p0, 0, 0, 0, 127, 0, 124);
;     p1 = __builtin_amdgcn_mfma_scale_f32_32x32x64_f8f6f4(a1, qf[s], p1, 0, 0, 0, 127, 0, 124); }
;   { const int c0 = hi * 2;
.Lmla_s5_cont:
	s_add_i32 s30, s30, 1
	s_cmpk_lt_u32 s30, 42
	s_cbranch_scc1 .Lmla_stag_loop
	ds_read_b128 v[114:117], v215 offset:24576
	ds_read_b128 v[118:121], v216 offset:24576
	ds_read_b128 v[222:225], v215 offset:28672
	ds_read_b128 v[226:229], v216 offset:28672
	v_exp_f32_e32 v0, v82
	v_exp_f32_e32 v177, v83
	v_exp_f32_e32 v179, v84
	v_exp_f32_e32 v254, v85
	v_add_f32_e32 v219, v0, v177
	v_cvt_pk_fp8_f32 v246, v0, v177
	v_add_f32_e32 v219, v179, v219
	v_add_f32_e32 v219, v254, v219
	v_cvt_pk_fp8_f32 v246, v179, v254 op_sel:[0,0,1]
	s_waitcnt lgkmcnt(2)
	v_mfma_scale_f32_32x32x64_f8f6f4 v[114:129], v[114:121], v[146:153], v[230:245], v194, v193 op_sel_hi:[0,0,0]
	v_exp_f32_e32 v0, v86
	v_exp_f32_e32 v177, v87
	v_exp_f32_e32 v179, v88
	v_exp_f32_e32 v254, v89
	v_add_f32_e32 v219, v0, v219
	v_add_f32_e32 v219, v177, v219
	v_cvt_pk_fp8_f32 v247, v0, v177
	v_add_f32_e32 v219, v179, v219
	v_add_f32_e32 v219, v254, v219
	v_cvt_pk_fp8_f32 v247, v179, v254 op_sel:[0,0,1]
	ds_read_b128 v[82:85], v213 offset:24576
	ds_read_b128 v[86:89], v214 offset:24576
	s_waitcnt lgkmcnt(2)
	v_mfma_scale_f32_32x32x64_f8f6f4 v[98:113], v[222:229], v[146:153], v[230:245], v194, v193 op_sel_hi:[0,0,0]
	ds_read_b128 v[222:225], v213 offset:28672
	ds_read_b128 v[226:229], v214 offset:28672
	v_exp_f32_e32 v0, v90
	v_exp_f32_e32 v177, v91
	v_exp_f32_e32 v179, v92
	v_exp_f32_e32 v254, v93
	v_add_f32_e32 v219, v0, v219
	v_add_f32_e32 v219, v177, v219
	v_cvt_pk_fp8_f32 v248, v0, v177
	v_add_f32_e32 v219, v179, v219
	v_add_f32_e32 v219, v254, v219
	v_cvt_pk_fp8_f32 v248, v179, v254 op_sel:[0,0,1]
	v_exp_f32_e32 v0, v94
	v_exp_f32_e32 v177, v95
	v_exp_f32_e32 v179, v96
	v_exp_f32_e32 v254, v97
	v_add_f32_e32 v219, v0, v219
	v_add_f32_e32 v219, v177, v219
	v_cvt_pk_fp8_f32 v249, v0, v177
	v_add_f32_e32 v219, v179, v219
	v_add_f32_e32 v219, v254, v219
	v_cvt_pk_fp8_f32 v249, v179, v254 op_sel:[0,0,1]
	ds_read_b128 v[90:93], v185 offset:36864
	ds_read_b128 v[94:97], v186 offset:36864
	s_waitcnt lgkmcnt(4)
	v_mfma_scale_f32_32x32x64_f8f6f4 v[114:129], v[82:89], v[138:145], v[114:129], v194, v193 op_sel_hi:[0,0,0]
	v_exp_f32_e32 v0, v66
	v_exp_f32_e32 v177, v67
	v_exp_f32_e32 v179, v68
	v_exp_f32_e32 v254, v69
	v_add_f32_e32 v219, v0, v219
	v_add_f32_e32 v219, v177, v219
	v_cvt_pk_fp8_f32 v250, v0, v177
	v_add_f32_e32 v219, v179, v219
	v_add_f32_e32 v219, v254, v219
	v_cvt_pk_fp8_f32 v250, v179, v254 op_sel:[0,0,1]
	s_waitcnt lgkmcnt(2)
	v_mfma_scale_f32_32x32x64_f8f6f4 v[98:113], v[222:229], v[138:145], v[98:113], v194, v193 op_sel_hi:[0,0,0]
	ds_read_b128 v[222:225], v185 offset:38912
	ds_read_b128 v[226:229], v186 offset:38912
	v_exp_f32_e32 v0, v70
	v_exp_f32_e32 v177, v71
	v_exp_f32_e32 v179, v72
	v_exp_f32_e32 v254, v73
	v_add_f32_e32 v219, v0, v219
	v_add_f32_e32 v219, v177, v219
	v_cvt_pk_fp8_f32 v251, v0, v177
	v_add_f32_e32 v219, v179, v219
	v_add_f32_e32 v219, v254, v219
	v_cvt_pk_fp8_f32 v251, v179, v254 op_sel:[0,0,1]
	v_exp_f32_e32 v0, v74
	v_exp_f32_e32 v177, v75
	v_exp_f32_e32 v179, v76
	v_exp_f32_e32 v254, v77
	v_add_f32_e32 v219, v0, v219
	v_add_f32_e32 v219, v177, v219
	v_cvt_pk_fp8_f32 v252, v0, v177
	v_add_f32_e32 v219, v179, v219
	v_add_f32_e32 v219, v254, v219
	v_cvt_pk_fp8_f32 v252, v179, v254 op_sel:[0,0,1]
	s_waitcnt lgkmcnt(2)
	v_mfma_scale_f32_32x32x64_f8f6f4 v[114:129], v[90:97], v[130:137], v[114:129], v194, v193 op_sel_hi:[0,0,0]
	v_exp_f32_e32 v0, v78
	v_exp_f32_e32 v177, v79
	v_exp_f32_e32 v179, v80
	v_exp_f32_e32 v254, v81
	v_add_f32_e32 v219, v0, v219
	v_add_f32_e32 v219, v177, v219
	v_cvt_pk_fp8_f32 v253, v0, v177
	v_add_f32_e32 v219, v179, v219
	v_add_f32_e32 v219, v254, v219
	v_cvt_pk_fp8_f32 v253, v179, v254 op_sel:[0,0,1]
	ds_read_b128 v[90:93], v185 offset:0
	ds_read_b128 v[94:97], v186 offset:0
	ds_read_b128 v[82:85], v185 offset:2048
	ds_read_b128 v[86:89], v186 offset:2048
	ds_read_b128 v[74:77], v185 offset:4096
	ds_read_b128 v[78:81], v186 offset:4096
	ds_read_b128 v[66:69], v185 offset:6144
	ds_read_b128 v[70:73], v186 offset:6144
	s_waitcnt lgkmcnt(8)
	v_mfma_scale_f32_32x32x64_f8f6f4 v[98:113], v[222:229], v[130:137], v[98:113], v194, v193 op_sel_hi:[0,0,0]
	v_mov_b32_e32 v0, v219
	s_nop 1
	v_permlane32_swap_b32_e32 v219, v0
	v_add_f32_e32 v219, v219, v0
	v_fma_f32 v209, v209, v218, v219
	v_max_f32_e32 v177, v114, v115
	v_max3_f32 v177, v177, v116, v117
	v_max3_f32 v177, v177, v118, v119
	v_max3_f32 v177, v177, v120, v121
	v_max3_f32 v177, v177, v122, v123
	v_max3_f32 v177, v177, v124, v125
	v_max3_f32 v177, v177, v126, v127
	v_max3_f32 v177, v177, v128, v129
	s_waitcnt vmcnt(0)
	ds_write_b128 v210, v[158:161] offset:43008
	ds_write_b128 v211, v[162:165] offset:51200
	s_waitcnt lgkmcnt(8)
	v_mfma_scale_f32_32x32x64_f8f6f4 v[50:65], v[246:253], v[90:97], v[50:65], v194, v194 op_sel_hi:[0,0,0]
	s_waitcnt lgkmcnt(6)
	v_mfma_scale_f32_32x32x64_f8f6f4 v[34:49], v[246:253], v[82:89], v[34:49], v194, v194 op_sel_hi:[0,0,0]
	s_waitcnt lgkmcnt(0)
	s_barrier
	global_load_dwordx4 v[158:161], v176, s[18:19]
	global_load_dwordx4 v[162:165], v178, s[16:17]
	v_add_u32_e32 v176, 0x2000, v176
	v_add_u32_e32 v178, 0x20000, v178
	s_waitcnt lgkmcnt(2)
	v_mfma_scale_f32_32x32x64_f8f6f4 v[18:33], v[246:253], v[74:81], v[18:33], v194, v194 op_sel_hi:[0,0,0]
	s_waitcnt lgkmcnt(0)
	v_mfma_scale_f32_32x32x64_f8f6f4 v[2:17], v[246:253], v[66:73], v[2:17], v194, v194 op_sel_hi:[0,0,0]
	v_max_f32_e32 v0, v98, v99
	v_max3_f32 v0, v0, v100, v101
	v_max3_f32 v0, v0, v102, v103
	v_max3_f32 v0, v0, v104, v105
	v_max3_f32 v0, v0, v106, v107
	v_max3_f32 v0, v0, v108, v109
	v_max3_f32 v0, v0, v110, v111
	v_max3_f32 v0, v0, v112, v113
	v_max_f32_e32 v177, v177, v0
	v_mov_b32_e32 v0, v177
	v_mov_b32_e32 v221, 1.0
	s_nop 0
	v_permlane32_swap_b32_e32 v177, v0
	v_max_f32_e32 v177, v177, v0
	v_cmp_ge_f32_e32 vcc, s90, v177
	s_cmp_eq_u64 vcc, exec
	s_cbranch_scc0 .Lmla_q0_newmax
; __device__ __forceinline__ void finishSM9(f32x16& p0, f32x16& p1, float alpha, float& l_reg, v8i32& p8) {
; #pragma unroll
;   for (int r = 0; r < 16; ++r) { p0[r] = __builtin_amdgcn_exp2f(p0[r]); p1[r] = __builtin_amdgcn_exp2f(p1[r]); }
;   float ps = 0;
; #pragma unroll
;   for (int r = 0; r < 16; ++r) ps += p0[r];
; #pragma unroll
;   for (int r = 0; r < 16; ++r) ps += p1[r];
;   { auto rr = __builtin_amdgcn_permlane32_swap(__float_as_uint(ps), __float_as_uint(ps), false, false);
;     ps = __uint_as_float(rr[0]) + __uint_as_float(rr[1]); }
;   l_reg = l_reg * alpha + ps;
; #pragma unroll
;   for (int g = 0; g < 4; ++g) {
;     int w = __builtin_amdgcn_cvt_pk_fp8_f32(p0[4 * g], p0[4 * g + 1], 0, false); p8[g] = __builtin_amdgcn_cvt_pk_fp8_f32(p0[4 * g + 2], p0[4 * g + 3], w, true);
;     int u = __builtin_amdgcn_cvt_pk_fp8_f32(p1[4 * g], p1[4 * g + 1], 0, false); p8[4 + g] = __builtin_amdgcn_cvt_pk_fp8_f32(p1[4 * g + 2], p1[4 * g + 3], u, true); }
; }
; __device__ __forceinline__ void pv8(f32x16* o, const char* Vt, const v8i32 p8, int r32, int hi) {
;   const int sw = (r32 >> 2) & 3, a0 = r32 * 64 + (((hi * 2) ^ sw) << 4), a1 = r32 * 64 + (((hi * 2 + 1) ^ sw) << 4);
; #pragma unroll
;   for (int d0 = 0; d0 < 4; ++d0) {
;     const v8i32 vf = cat8(*reinterpret_cast<const v4i32*>(Vt + d0 * 2048 + a0), *reinterpret_cast<const v4i32*>(Vt + d0 * 2048 + a1));
;     o[d0] = __builtin_amdgcn_mfma_scale_f32_32x32x64_f8f6f4(p8, vf, o[d0], 0, 0, 0, 127, 0, 127); }
; }
; __device__ __forceinline__ void qkt9(f32x16& p0, f32x16& p1, const char* Kn, const char* Kr, const v8i32* qf, const float init, int r32, int hi) {
; #pragma unroll
;   for (int r = 0; r < 16; ++r) { p0[r] = init; p1[r] = init; }
; #pragma unroll
;   for (int s = 0; s < 2; ++s) { const int c0 = s * 4 + hi * 2;
;     const v8i32 a0 = cat8(*reinterpret_cast<const v4i32*>(Kn + KN8SW(r32, c0)), *reinterpret_cast<const v4i32*>(Kn + KN8SW(r32, c0 + 1)));
;     const v8i32 a1 = cat8(*reinterpret_cast<const v4i32*>(Kn + 4096 + KN8SW(r32, c0)), *reinterpret_cast<const v4i32*>(Kn + 4096 + KN8SW(r32, c0 + 1)));
;     p0 = __builtin_amdgcn_mfma_scale_f32_32x32x64_f8f6f4(a0, qf[s], p0, 0, 0, 0, 127, 0, 124);
;     p1 = __builtin_amdgcn_mfma_scale_f32_32x32x64_f8f6f4(a1, qf[s], p1, 0, 0, 0, 127, 0, 124); }
;   { const int c0 = hi * 2;
.Lmla_q0_cont:
	ds_read_b128 v[82:85], v215 offset:51200
	ds_read_b128 v[86:89], v216 offset:51200
	ds_read_b128 v[222:225], v215 offset:55296
	ds_read_b128 v[226:229], v216 offset:55296
	v_exp_f32_e32 v0, v114
	v_exp_f32_e32 v177, v115
	v_exp_f32_e32 v179, v116
	v_exp_f32_e32 v254, v117
	v_add_f32_e32 v219, v0, v177
	v_cvt_pk_fp8_f32 v246, v0, v177
	v_add_f32_e32 v219, v179, v219
	v_add_f32_e32 v219, v254, v219
	v_cvt_pk_fp8_f32 v246, v179, v254 op_sel:[0,0,1]
	s_waitcnt lgkmcnt(2)
	v_mfma_scale_f32_32x32x64_f8f6f4 v[82:97], v[82:89], v[146:153], v[230:245], v194, v193 op_sel_hi:[0,0,0]
	v_exp_f32_e32 v0, v118
	v_exp_f32_e32 v177, v119
	v_exp_f32_e32 v179, v120
	v_exp_f32_e32 v254, v121
	v_add_f32_e32 v219, v0, v219
	v_add_f32_e32 v219, v177, v219
	v_cvt_pk_fp8_f32 v247, v0, v177
	v_add_f32_e32 v219, v179, v219
	v_add_f32_e32 v219, v254, v219
	v_cvt_pk_fp8_f32 v247, v179, v254 op_sel:[0,0,1]
	ds_read_b128 v[114:117], v213 offset:51200
	ds_read_b128 v[118:121], v214 offset:51200
	s_waitcnt lgkmcnt(2)
	v_mfma_scale_f32_32x32x64_f8f6f4 v[66:81], v[222:229], v[146:153], v[230:245], v194, v193 op_sel_hi:[0,0,0]
	ds_read_b128 v[222:225], v213 offset:55296
	ds_read_b128 v[226:229], v214 offset:55296
	v_exp_f32_e32 v0, v122
	v_exp_f32_e32 v177, v123
	v_exp_f32_e32 v179, v124
	v_exp_f32_e32 v254, v125
	v_add_f32_e32 v219, v0, v219
	v_add_f32_e32 v219, v177, v219
	v_cvt_pk_fp8_f32 v248, v0, v177
	v_add_f32_e32 v219, v179, v219
	v_add_f32_e32 v219, v254, v219
	v_cvt_pk_fp8_f32 v248, v179, v254 op_sel:[0,0,1]
	v_exp_f32_e32 v0, v126
	v_exp_f32_e32 v177, v127
	v_exp_f32_e32 v179, v128
	v_exp_f32_e32 v254, v129
	v_add_f32_e32 v219, v0, v219
	v_add_f32_e32 v219, v177, v219
	v_cvt_pk_fp8_f32 v249, v0, v177
	v_add_f32_e32 v219, v179, v219
	v_add_f32_e32 v219, v254, v219
	v_cvt_pk_fp8_f32 v249, v179, v254 op_sel:[0,0,1]
	ds_read_b128 v[122:125], v185 offset:59392
	ds_read_b128 v[126:129], v186 offset:59392
	s_waitcnt lgkmcnt(4)
	v_mfma_scale_f32_32x32x64_f8f6f4 v[82:97], v[114:121], v[138:145], v[82:97], v194, v193 op_sel_hi:[0,0,0]
	v_exp_f32_e32 v0, v98
	v_exp_f32_e32 v177, v99
	v_exp_f32_e32 v179, v100
	v_exp_f32_e32 v254, v101
	v_add_f32_e32 v219, v0, v219
	v_add_f32_e32 v219, v177, v219
	v_cvt_pk_fp8_f32 v250, v0, v177
	v_add_f32_e32 v219, v179, v219
	v_add_f32_e32 v219, v254, v219
	v_cvt_pk_fp8_f32 v250, v179, v254 op_sel:[0,0,1]
	s_waitcnt lgkmcnt(2)
	v_mfma_scale_f32_32x32x64_f8f6f4 v[66:81], v[222:229], v[138:145], v[66:81], v194, v193 op_sel_hi:[0,0,0]
	ds_read_b128 v[222:225], v185 offset:61440
	ds_read_b128 v[226:229], v186 offset:61440
	v_exp_f32_e32 v0, v102
	v_exp_f32_e32 v177, v103
	v_exp_f32_e32 v179, v104
	v_exp_f32_e32 v254, v105
	v_add_f32_e32 v219, v0, v219
	v_add_f32_e32 v219, v177, v219
	v_cvt_pk_fp8_f32 v251, v0, v177
	v_add_f32_e32 v219, v179, v219
	v_add_f32_e32 v219, v254, v219
	v_cvt_pk_fp8_f32 v251, v179, v254 op_sel:[0,0,1]
	v_exp_f32_e32 v0, v106
	v_exp_f32_e32 v177, v107
	v_exp_f32_e32 v179, v108
	v_exp_f32_e32 v254, v109
	v_add_f32_e32 v219, v0, v219
	v_add_f32_e32 v219, v177, v219
	v_cvt_pk_fp8_f32 v252, v0, v177
	v_add_f32_e32 v219, v179, v219
	v_add_f32_e32 v219, v254, v219
	v_cvt_pk_fp8_f32 v252, v179, v254 op_sel:[0,0,1]
	s_waitcnt lgkmcnt(2)
	v_mfma_scale_f32_32x32x64_f8f6f4 v[82:97], v[122:129], v[130:137], v[82:97], v194, v193 op_sel_hi:[0,0,0]
	v_exp_f32_e32 v0, v110
	v_exp_f32_e32 v177, v111
	v_exp_f32_e32 v179, v112
	v_exp_f32_e32 v254, v113
	v_add_f32_e32 v219, v0, v219
	v_add_f32_e32 v219, v177, v219
	v_cvt_pk_fp8_f32 v253, v0, v177
	v_add_f32_e32 v219, v179, v219
	v_add_f32_e32 v219, v254, v219
	v_cvt_pk_fp8_f32 v253, v179, v254 op_sel:[0,0,1]
	ds_read_b128 v[122:125], v185 offset:8192
	ds_read_b128 v[126:129], v186 offset:8192
	ds_read_b128 v[114:117], v185 offset:10240
	ds_read_b128 v[118:121], v186 offset:10240
	ds_read_b128 v[106:109], v185 offset:12288
	ds_read_b128 v[110:113], v186 offset:12288
	ds_read_b128 v[98:101], v185 offset:14336
	ds_read_b128 v[102:105], v186 offset:14336
	s_waitcnt lgkmcnt(8)
	v_mfma_scale_f32_32x32x64_f8f6f4 v[66:81], v[222:229], v[130:137], v[66:81], v194, v193 op_sel_hi:[0,0,0]
	v_mov_b32_e32 v0, v219
	s_nop 1
	v_permlane32_swap_b32_e32 v219, v0
	v_add_f32_e32 v219, v219, v0
	v_fma_f32 v209, v209, v221, v219
	v_max_f32_e32 v177, v82, v83
	v_max3_f32 v177, v177, v84, v85
	v_max3_f32 v177, v177, v86, v87
	v_max3_f32 v177, v177, v88, v89
	v_max3_f32 v177, v177, v90, v91
	v_max3_f32 v177, v177, v92, v93
	v_max3_f32 v177, v177, v94, v95
	v_max3_f32 v177, v177, v96, v97
	s_waitcnt vmcnt(0)
	ds_write_b128 v210, v[158:161]
	ds_write_b128 v211, v[162:165] offset:16384
	s_waitcnt lgkmcnt(8)
	v_mfma_scale_f32_32x32x64_f8f6f4 v[50:65], v[246:253], v[122:129], v[50:65], v194, v194 op_sel_hi:[0,0,0]
	s_waitcnt lgkmcnt(6)
	v_mfma_scale_f32_32x32x64_f8f6f4 v[34:49], v[246:253], v[114:121], v[34:49], v194, v194 op_sel_hi:[0,0,0]
	s_waitcnt lgkmcnt(0)
	s_barrier
	s_waitcnt lgkmcnt(2)
	v_mfma_scale_f32_32x32x64_f8f6f4 v[18:33], v[246:253], v[106:113], v[18:33], v194, v194 op_sel_hi:[0,0,0]
	s_waitcnt lgkmcnt(0)
	v_mfma_scale_f32_32x32x64_f8f6f4 v[2:17], v[246:253], v[98:105], v[2:17], v194, v194 op_sel_hi:[0,0,0]
	v_max_f32_e32 v0, v66, v67
	v_max3_f32 v0, v0, v68, v69
	v_max3_f32 v0, v0, v70, v71
	v_max3_f32 v0, v0, v72, v73
	v_max3_f32 v0, v0, v74, v75
	v_max3_f32 v0, v0, v76, v77
	v_max3_f32 v0, v0, v78, v79
	v_max3_f32 v0, v0, v80, v81
	v_max_f32_e32 v177, v177, v0
	v_mov_b32_e32 v0, v177
	v_mov_b32_e32 v218, 1.0
	s_nop 0
	v_permlane32_swap_b32_e32 v177, v0
	v_max_f32_e32 v177, v177, v0
	v_cmp_ge_f32_e32 vcc, s90, v177
	s_cmp_eq_u64 vcc, exec
	s_cbranch_scc0 .Lmla_q1_newmax
